# GEMM K-loops: back-edge SALU rotated ahead of the loop-back barrier; redundant lgkmcnt(0) after the MMA-entry barrier deleted
# baseline (speedup 1.0000x reference)
.LBB0_309:
	ds_read_b128 v[146:149], v153
	ds_read_b128 v[160:163], v153 offset:1024
	ds_read_b128 v[164:167], v153 offset:2048
	ds_read_b128 v[168:171], v153 offset:3072
	ds_read_b128 v[172:175], v154
	ds_read_b128 v[176:179], v154 offset:1024
	ds_read_b128 v[180:183], v154 offset:2048
	ds_read_b128 v[184:187], v154 offset:3072
	s_add_u32 s34, s6, 0xfff00080
	s_addc_u32 s35, s7, -1
	s_cmp_eq_u32 s59, 60
	s_cselect_b32 s37, s5, s35
	s_cselect_b32 s36, s25, s34
	s_cselect_b32 s35, s23, s58
	s_cselect_b32 s34, s56, s57
	v_lshl_add_u64 v[220:221], s[6:7], 0, v[138:139]
	s_add_i32 m0, s31, 0xc000
	ds_read_b128 v[188:191], v155
	ds_read_b128 v[192:195], v155 offset:1024
	ds_read_b128 v[196:199], v155 offset:2048
	ds_read_b128 v[200:203], v155 offset:3072
	ds_read_b128 v[204:207], v155 offset:4096
	ds_read_b128 v[208:211], v155 offset:5120
	ds_read_b128 v[212:215], v155 offset:6144
	ds_read_b128 v[216:219], v155 offset:7168
	global_load_lds_dwordx4 v[220:221], off
	v_lshl_add_u64 v[220:221], s[6:7], 0, v[136:137]
	s_add_i32 m0, s31, 0xe000
	s_nop 0
	global_load_lds_dwordx4 v[220:221], off
	s_waitcnt vmcnt(8)
	s_waitcnt lgkmcnt(0)
	s_barrier
	s_setprio 1
	v_mfma_f32_16x16x32_bf16 v[124:127], v[146:149], v[188:191], v[124:127]
	v_mfma_f32_16x16x32_bf16 v[120:123], v[164:167], v[188:191], v[120:123]
	v_mfma_f32_16x16x32_bf16 v[108:111], v[146:149], v[196:199], v[108:111]
	v_mfma_f32_16x16x32_bf16 v[104:107], v[164:167], v[196:199], v[104:107]
	v_mfma_f32_16x16x32_bf16 v[92:95], v[146:149], v[204:207], v[92:95]
	v_mfma_f32_16x16x32_bf16 v[88:91], v[164:167], v[204:207], v[88:91]
	v_mfma_f32_16x16x32_bf16 v[76:79], v[146:149], v[212:215], v[76:79]
	v_mfma_f32_16x16x32_bf16 v[72:75], v[164:167], v[212:215], v[72:75]
	v_mfma_f32_16x16x32_bf16 v[124:127], v[160:163], v[192:195], v[124:127]
	v_mfma_f32_16x16x32_bf16 v[120:123], v[168:171], v[192:195], v[120:123]
	v_mfma_f32_16x16x32_bf16 v[108:111], v[160:163], v[200:203], v[108:111]
	v_mfma_f32_16x16x32_bf16 v[104:107], v[168:171], v[200:203], v[104:107]
	v_mfma_f32_16x16x32_bf16 v[92:95], v[160:163], v[208:211], v[92:95]
	v_mfma_f32_16x16x32_bf16 v[88:91], v[168:171], v[208:211], v[88:91]
	v_mfma_f32_16x16x32_bf16 v[76:79], v[160:163], v[216:219], v[76:79]
	v_mfma_f32_16x16x32_bf16 v[72:75], v[168:171], v[216:219], v[72:75]
	s_setprio 0
	s_setprio 1
	v_mfma_f32_16x16x32_bf16 v[116:119], v[172:175], v[188:191], v[116:119]
	v_mfma_f32_16x16x32_bf16 v[112:115], v[180:183], v[188:191], v[112:115]
	v_mfma_f32_16x16x32_bf16 v[100:103], v[172:175], v[196:199], v[100:103]
	v_mfma_f32_16x16x32_bf16 v[96:99], v[180:183], v[196:199], v[96:99]
	v_mfma_f32_16x16x32_bf16 v[84:87], v[172:175], v[204:207], v[84:87]
	v_mfma_f32_16x16x32_bf16 v[80:83], v[180:183], v[204:207], v[80:83]
	v_mfma_f32_16x16x32_bf16 v[68:71], v[172:175], v[212:215], v[68:71]
	v_mfma_f32_16x16x32_bf16 v[64:67], v[180:183], v[212:215], v[64:67]
	v_mfma_f32_16x16x32_bf16 v[116:119], v[176:179], v[192:195], v[116:119]
	v_mfma_f32_16x16x32_bf16 v[112:115], v[184:187], v[192:195], v[112:115]
	v_mfma_f32_16x16x32_bf16 v[100:103], v[176:179], v[200:203], v[100:103]
	v_mfma_f32_16x16x32_bf16 v[96:99], v[184:187], v[200:203], v[96:99]
	v_mfma_f32_16x16x32_bf16 v[84:87], v[176:179], v[208:211], v[84:87]
	v_mfma_f32_16x16x32_bf16 v[80:83], v[184:187], v[208:211], v[80:83]
	v_mfma_f32_16x16x32_bf16 v[68:71], v[176:179], v[216:219], v[68:71]
	v_mfma_f32_16x16x32_bf16 v[64:67], v[184:187], v[216:219], v[64:67]
	s_setprio 0
	s_barrier
	s_add_i32 s60, s52, s42
	v_lshl_add_u64 v[220:221], s[34:35], 0, v[130:131]
	s_mov_b32 m0, s60
	ds_read_b128 v[188:191], v155 offset:16384
	ds_read_b128 v[192:195], v155 offset:17408
	ds_read_b128 v[196:199], v155 offset:18432
	ds_read_b128 v[200:203], v155 offset:19456
	ds_read_b128 v[204:207], v155 offset:20480
	ds_read_b128 v[208:211], v155 offset:21504
	ds_read_b128 v[212:215], v155 offset:22528
	ds_read_b128 v[216:219], v155 offset:23552
	global_load_lds_dwordx4 v[220:221], off
	s_add_i32 m0, s60, 0x2000
	s_add_u32 s60, s34, 0x100000
	v_lshl_add_u64 v[222:223], s[34:35], 0, v[134:135]
	s_addc_u32 s61, s35, 0
	s_add_i32 s62, s53, s42
	global_load_lds_dwordx4 v[222:223], off
	v_lshl_add_u64 v[224:225], s[60:61], 0, v[130:131]
	s_mov_b32 m0, s62
	v_lshl_add_u64 v[226:227], s[36:37], 0, v[132:133]
	global_load_lds_dwordx4 v[224:225], off
	v_lshl_add_u64 v[224:225], s[60:61], 0, v[134:135]
	s_add_i32 m0, s62, 0x2000
	s_nop 0
	global_load_lds_dwordx4 v[224:225], off
	v_lshl_add_u64 v[224:225], s[36:37], 0, v[128:129]
	s_mov_b32 m0, s31
	s_nop 0
	global_load_lds_dwordx4 v[224:225], off
	s_mov_b32 m0, s43
	s_nop 0
	global_load_lds_dwordx4 v[226:227], off
	s_waitcnt vmcnt(8)
	s_waitcnt lgkmcnt(0)
	s_barrier
	s_setprio 1
	v_mfma_f32_16x16x32_bf16 v[60:63], v[146:149], v[188:191], v[60:63]
	v_mfma_f32_16x16x32_bf16 v[56:59], v[164:167], v[188:191], v[56:59]
	v_mfma_f32_16x16x32_bf16 v[44:47], v[146:149], v[196:199], v[44:47]
	v_mfma_f32_16x16x32_bf16 v[40:43], v[164:167], v[196:199], v[40:43]
	v_mfma_f32_16x16x32_bf16 v[28:31], v[146:149], v[204:207], v[28:31]
	v_mfma_f32_16x16x32_bf16 v[24:27], v[164:167], v[204:207], v[24:27]
	v_mfma_f32_16x16x32_bf16 v[12:15], v[146:149], v[212:215], v[12:15]
	v_mfma_f32_16x16x32_bf16 v[8:11], v[164:167], v[212:215], v[8:11]
	v_mfma_f32_16x16x32_bf16 v[60:63], v[160:163], v[192:195], v[60:63]
	v_mfma_f32_16x16x32_bf16 v[56:59], v[168:171], v[192:195], v[56:59]
	v_mfma_f32_16x16x32_bf16 v[44:47], v[160:163], v[200:203], v[44:47]
	v_mfma_f32_16x16x32_bf16 v[40:43], v[168:171], v[200:203], v[40:43]
	v_mfma_f32_16x16x32_bf16 v[28:31], v[160:163], v[208:211], v[28:31]
	v_mfma_f32_16x16x32_bf16 v[24:27], v[168:171], v[208:211], v[24:27]
	v_mfma_f32_16x16x32_bf16 v[12:15], v[160:163], v[216:219], v[12:15]
	v_mfma_f32_16x16x32_bf16 v[8:11], v[168:171], v[216:219], v[8:11]
	s_setprio 0
	s_setprio 1
	v_mfma_f32_16x16x32_bf16 v[52:55], v[172:175], v[188:191], v[52:55]
	v_mfma_f32_16x16x32_bf16 v[48:51], v[180:183], v[188:191], v[48:51]
	v_mfma_f32_16x16x32_bf16 v[36:39], v[172:175], v[196:199], v[36:39]
	v_mfma_f32_16x16x32_bf16 v[32:35], v[180:183], v[196:199], v[32:35]
	v_mfma_f32_16x16x32_bf16 v[20:23], v[172:175], v[204:207], v[20:23]
	v_mfma_f32_16x16x32_bf16 v[16:19], v[180:183], v[204:207], v[16:19]
	v_mfma_f32_16x16x32_bf16 v[4:7], v[172:175], v[212:215], v[4:7]
	v_mfma_f32_16x16x32_bf16 v[0:3], v[180:183], v[212:215], v[0:3]
	v_mfma_f32_16x16x32_bf16 v[52:55], v[176:179], v[192:195], v[52:55]
	v_mfma_f32_16x16x32_bf16 v[48:51], v[184:187], v[192:195], v[48:51]
	v_mfma_f32_16x16x32_bf16 v[36:39], v[176:179], v[200:203], v[36:39]
	v_mfma_f32_16x16x32_bf16 v[32:35], v[184:187], v[200:203], v[32:35]
	v_mfma_f32_16x16x32_bf16 v[20:23], v[176:179], v[208:211], v[20:23]
	v_mfma_f32_16x16x32_bf16 v[16:19], v[184:187], v[208:211], v[16:19]
	v_mfma_f32_16x16x32_bf16 v[4:7], v[176:179], v[216:219], v[4:7]
	v_mfma_f32_16x16x32_bf16 v[0:3], v[184:187], v[216:219], v[0:3]
	s_setprio 0
	s_barrier
	s_add_i32 s60, 0, 0x18000
	v_add_u32_e32 v144, s60, v151
	s_add_i32 s61, 0, 0x1c000
	ds_read_b128 v[146:149], v144
	ds_read_b128 v[160:163], v144 offset:1024
	ds_read_b128 v[164:167], v144 offset:2048
	ds_read_b128 v[168:171], v144 offset:3072
	v_add_u32_e32 v144, s61, v151
	ds_read_b128 v[172:175], v144
	ds_read_b128 v[176:179], v144 offset:1024
	ds_read_b128 v[180:183], v144 offset:2048
	ds_read_b128 v[184:187], v144 offset:3072
	s_add_u32 s36, s36, 0x100000
	s_addc_u32 s37, s37, 0
	s_mov_b32 m0, s44
	v_lshl_add_u64 v[228:229], s[36:37], 0, v[128:129]
	ds_read_b128 v[188:191], v155 offset:32768
	ds_read_b128 v[192:195], v155 offset:33792
	ds_read_b128 v[196:199], v155 offset:34816
	ds_read_b128 v[200:203], v155 offset:35840
	ds_read_b128 v[204:207], v155 offset:36864
	ds_read_b128 v[208:211], v155 offset:37888
	ds_read_b128 v[212:215], v155 offset:38912
	ds_read_b128 v[216:219], v155 offset:39936
	global_load_lds_dwordx4 v[228:229], off
	v_lshl_add_u64 v[228:229], s[36:37], 0, v[132:133]
	s_mov_b32 m0, s45
	s_nop 0
	global_load_lds_dwordx4 v[228:229], off
	s_waitcnt vmcnt(8)
	s_waitcnt lgkmcnt(0)
	s_barrier
	s_setprio 1
	v_mfma_f32_16x16x32_bf16 v[124:127], v[146:149], v[188:191], v[124:127]
	v_mfma_f32_16x16x32_bf16 v[120:123], v[164:167], v[188:191], v[120:123]
	v_mfma_f32_16x16x32_bf16 v[108:111], v[146:149], v[196:199], v[108:111]
	v_mfma_f32_16x16x32_bf16 v[104:107], v[164:167], v[196:199], v[104:107]
	v_mfma_f32_16x16x32_bf16 v[92:95], v[146:149], v[204:207], v[92:95]
	v_mfma_f32_16x16x32_bf16 v[88:91], v[164:167], v[204:207], v[88:91]
	v_mfma_f32_16x16x32_bf16 v[76:79], v[146:149], v[212:215], v[76:79]
	v_mfma_f32_16x16x32_bf16 v[72:75], v[164:167], v[212:215], v[72:75]
	v_mfma_f32_16x16x32_bf16 v[124:127], v[160:163], v[192:195], v[124:127]
	v_mfma_f32_16x16x32_bf16 v[120:123], v[168:171], v[192:195], v[120:123]
	v_mfma_f32_16x16x32_bf16 v[108:111], v[160:163], v[200:203], v[108:111]
	v_mfma_f32_16x16x32_bf16 v[104:107], v[168:171], v[200:203], v[104:107]
	v_mfma_f32_16x16x32_bf16 v[92:95], v[160:163], v[208:211], v[92:95]
	v_mfma_f32_16x16x32_bf16 v[88:91], v[168:171], v[208:211], v[88:91]
	v_mfma_f32_16x16x32_bf16 v[76:79], v[160:163], v[216:219], v[76:79]
	v_mfma_f32_16x16x32_bf16 v[72:75], v[168:171], v[216:219], v[72:75]
	s_setprio 0
	s_setprio 1
	v_mfma_f32_16x16x32_bf16 v[116:119], v[172:175], v[188:191], v[116:119]
	v_mfma_f32_16x16x32_bf16 v[112:115], v[180:183], v[188:191], v[112:115]
	v_mfma_f32_16x16x32_bf16 v[100:103], v[172:175], v[196:199], v[100:103]
	v_mfma_f32_16x16x32_bf16 v[96:99], v[180:183], v[196:199], v[96:99]
	v_mfma_f32_16x16x32_bf16 v[84:87], v[172:175], v[204:207], v[84:87]
	v_mfma_f32_16x16x32_bf16 v[80:83], v[180:183], v[204:207], v[80:83]
	v_mfma_f32_16x16x32_bf16 v[68:71], v[172:175], v[212:215], v[68:71]
	v_mfma_f32_16x16x32_bf16 v[64:67], v[180:183], v[212:215], v[64:67]
	v_mfma_f32_16x16x32_bf16 v[116:119], v[176:179], v[192:195], v[116:119]
	v_mfma_f32_16x16x32_bf16 v[112:115], v[184:187], v[192:195], v[112:115]
	v_mfma_f32_16x16x32_bf16 v[100:103], v[176:179], v[200:203], v[100:103]
	v_mfma_f32_16x16x32_bf16 v[96:99], v[184:187], v[200:203], v[96:99]
	v_mfma_f32_16x16x32_bf16 v[84:87], v[176:179], v[208:211], v[84:87]
	v_mfma_f32_16x16x32_bf16 v[80:83], v[184:187], v[208:211], v[80:83]
	v_mfma_f32_16x16x32_bf16 v[68:71], v[176:179], v[216:219], v[68:71]
	v_mfma_f32_16x16x32_bf16 v[64:67], v[184:187], v[216:219], v[64:67]
	s_setprio 0
	s_barrier
	s_add_i32 s36, s60, s42
	v_lshl_add_u64 v[220:221], v[220:221], 0, s[16:17]
	s_mov_b32 m0, s36
	ds_read_b128 v[188:191], v155 offset:49152
	ds_read_b128 v[192:195], v155 offset:50176
	ds_read_b128 v[196:199], v155 offset:51200
	ds_read_b128 v[200:203], v155 offset:52224
	ds_read_b128 v[204:207], v155 offset:53248
	ds_read_b128 v[208:211], v155 offset:54272
	ds_read_b128 v[212:215], v155 offset:55296
	ds_read_b128 v[216:219], v155 offset:56320
	global_load_lds_dwordx4 v[220:221], off
	s_add_i32 m0, s36, 0x2000
	s_add_u32 s34, s34, 0x100080
	v_lshl_add_u64 v[220:221], v[222:223], 0, s[16:17]
	s_addc_u32 s35, s35, 0
	s_add_i32 s36, s61, s42
	global_load_lds_dwordx4 v[220:221], off
	v_lshl_add_u64 v[220:221], s[34:35], 0, v[130:131]
	s_mov_b32 m0, s36
	s_nop 0
	global_load_lds_dwordx4 v[220:221], off
	v_lshl_add_u64 v[220:221], s[34:35], 0, v[134:135]
	s_add_i32 m0, s36, 0x2000
	s_nop 0
	global_load_lds_dwordx4 v[220:221], off
	v_lshl_add_u64 v[220:221], v[224:225], 0, s[16:17]
	s_mov_b32 m0, s47
	s_nop 0
	global_load_lds_dwordx4 v[220:221], off
	v_lshl_add_u64 v[220:221], v[226:227], 0, s[16:17]
	s_mov_b32 m0, s48
	s_nop 0
	global_load_lds_dwordx4 v[220:221], off
	s_waitcnt vmcnt(8)
	s_waitcnt lgkmcnt(0)
	s_barrier
	s_setprio 1
	v_mfma_f32_16x16x32_bf16 v[60:63], v[146:149], v[188:191], v[60:63]
	v_mfma_f32_16x16x32_bf16 v[56:59], v[164:167], v[188:191], v[56:59]
	v_mfma_f32_16x16x32_bf16 v[44:47], v[146:149], v[196:199], v[44:47]
	v_mfma_f32_16x16x32_bf16 v[40:43], v[164:167], v[196:199], v[40:43]
	v_mfma_f32_16x16x32_bf16 v[28:31], v[146:149], v[204:207], v[28:31]
	v_mfma_f32_16x16x32_bf16 v[24:27], v[164:167], v[204:207], v[24:27]
	v_mfma_f32_16x16x32_bf16 v[12:15], v[146:149], v[212:215], v[12:15]
	v_mfma_f32_16x16x32_bf16 v[8:11], v[164:167], v[212:215], v[8:11]
	v_mfma_f32_16x16x32_bf16 v[60:63], v[160:163], v[192:195], v[60:63]
	v_mfma_f32_16x16x32_bf16 v[56:59], v[168:171], v[192:195], v[56:59]
	v_mfma_f32_16x16x32_bf16 v[44:47], v[160:163], v[200:203], v[44:47]
	v_mfma_f32_16x16x32_bf16 v[40:43], v[168:171], v[200:203], v[40:43]
	v_mfma_f32_16x16x32_bf16 v[28:31], v[160:163], v[208:211], v[28:31]
	v_mfma_f32_16x16x32_bf16 v[24:27], v[168:171], v[208:211], v[24:27]
	v_mfma_f32_16x16x32_bf16 v[12:15], v[160:163], v[216:219], v[12:15]
	v_mfma_f32_16x16x32_bf16 v[8:11], v[168:171], v[216:219], v[8:11]
	s_setprio 0
	s_setprio 1
	v_mfma_f32_16x16x32_bf16 v[52:55], v[172:175], v[188:191], v[52:55]
	v_mfma_f32_16x16x32_bf16 v[48:51], v[180:183], v[188:191], v[48:51]
	v_mfma_f32_16x16x32_bf16 v[36:39], v[172:175], v[196:199], v[36:39]
	v_mfma_f32_16x16x32_bf16 v[32:35], v[180:183], v[196:199], v[32:35]
	v_mfma_f32_16x16x32_bf16 v[20:23], v[172:175], v[204:207], v[20:23]
	v_mfma_f32_16x16x32_bf16 v[16:19], v[180:183], v[204:207], v[16:19]
	v_mfma_f32_16x16x32_bf16 v[4:7], v[172:175], v[212:215], v[4:7]
	v_mfma_f32_16x16x32_bf16 v[0:3], v[180:183], v[212:215], v[0:3]
	v_mfma_f32_16x16x32_bf16 v[52:55], v[176:179], v[192:195], v[52:55]
	v_mfma_f32_16x16x32_bf16 v[48:51], v[184:187], v[192:195], v[48:51]
	v_mfma_f32_16x16x32_bf16 v[36:39], v[176:179], v[200:203], v[36:39]
	v_mfma_f32_16x16x32_bf16 v[32:35], v[184:187], v[200:203], v[32:35]
	v_mfma_f32_16x16x32_bf16 v[20:23], v[176:179], v[208:211], v[20:23]
	v_mfma_f32_16x16x32_bf16 v[16:19], v[184:187], v[208:211], v[16:19]
	v_mfma_f32_16x16x32_bf16 v[4:7], v[176:179], v[216:219], v[4:7]
	v_mfma_f32_16x16x32_bf16 v[0:3], v[184:187], v[216:219], v[0:3]
	s_setprio 0
	s_add_i32 s59, s59, 2
	s_add_u32 s57, s57, 0x100
	s_addc_u32 s58, s58, 0
	s_add_u32 s6, s6, 0x100
	s_addc_u32 s7, s7, 0
	s_cmp_gt_u32 s59, 61
	s_barrier
	s_cbranch_scc0 .LBB0_309
	s_and_b64 vcc, exec, s[18:19]
	s_cbranch_vccz .LBB0_312
	s_barrier

.LBB0_618:
	s_ashr_i32 s35, s34, 31
	s_lshl_b64 s[36:37], s[34:35], 19
	s_add_u32 s31, s33, s36
	s_addc_u32 s35, s50, s37
	s_ashr_i32 s36, s30, 3
	ds_read_b128 v[0:3], v155
	ds_read_b128 v[4:7], v155 offset:1024
	ds_read_b128 v[8:11], v155 offset:2048
	ds_read_b128 v[12:15], v155 offset:3072
	ds_read_b128 v[16:19], v156
	ds_read_b128 v[20:23], v156 offset:1024
	ds_read_b128 v[24:27], v156 offset:2048
	ds_read_b128 v[28:31], v156 offset:3072
	s_ashr_i32 s37, s36, 31
	s_lshl_b64 s[36:37], s[36:37], 9
	s_add_u32 s36, s31, s36
	s_addc_u32 s37, s35, s37
	s_and_b64 s[38:39], s[2:3], exec
	s_cselect_b32 s49, s37, s43
	s_cselect_b32 s48, s36, s42
	s_ashr_i32 s31, s30, 31
	s_lshl_b64 s[38:39], s[30:31], 17
	s_add_u32 s38, s51, s38
	s_addc_u32 s39, s52, s39
	s_and_b64 s[46:47], s[2:3], exec
	s_cselect_b32 s47, s39, s45
	s_cselect_b32 s46, s38, s44
	s_add_u32 s74, s42, 0x40080
	s_addc_u32 s75, s43, 0
	s_add_i32 s77, s60, 0xc000
	v_lshl_add_u64 v[64:65], s[74:75], 0, v[134:135]
	s_mov_b32 m0, s77
	s_add_i32 s31, s60, 0xe000
	ds_read_b128 v[32:35], v157
	ds_read_b128 v[36:39], v157 offset:1024
	ds_read_b128 v[40:43], v157 offset:2048
	ds_read_b128 v[44:47], v157 offset:3072
	ds_read_b128 v[48:51], v157 offset:4096
	ds_read_b128 v[52:55], v157 offset:5120
	ds_read_b128 v[56:59], v157 offset:6144
	ds_read_b128 v[60:63], v157 offset:7168
	global_load_lds_dwordx4 v[64:65], off
	v_lshl_add_u64 v[64:65], s[74:75], 0, v[130:131]
	s_mov_b32 m0, s31
	s_nop 0
	global_load_lds_dwordx4 v[64:65], off
	s_waitcnt vmcnt(8)
	s_waitcnt lgkmcnt(0)
	s_barrier
	s_setprio 1
	v_mfma_f32_16x16x32_bf16 v[64:67], v[0:3], v[32:35], 0
	v_mfma_f32_16x16x32_bf16 v[68:71], v[8:11], v[32:35], 0
	v_mfma_f32_16x16x32_bf16 v[72:75], v[0:3], v[40:43], 0
	v_mfma_f32_16x16x32_bf16 v[76:79], v[8:11], v[40:43], 0
	v_mfma_f32_16x16x32_bf16 v[80:83], v[0:3], v[48:51], 0
	v_mfma_f32_16x16x32_bf16 v[84:87], v[8:11], v[48:51], 0
	v_mfma_f32_16x16x32_bf16 v[88:91], v[0:3], v[56:59], 0
	v_mfma_f32_16x16x32_bf16 v[92:95], v[8:11], v[56:59], 0
	v_mfma_f32_16x16x32_bf16 v[64:67], v[4:7], v[36:39], v[64:67]
	v_mfma_f32_16x16x32_bf16 v[68:71], v[12:15], v[36:39], v[68:71]
	v_mfma_f32_16x16x32_bf16 v[72:75], v[4:7], v[44:47], v[72:75]
	v_mfma_f32_16x16x32_bf16 v[76:79], v[12:15], v[44:47], v[76:79]
	v_mfma_f32_16x16x32_bf16 v[80:83], v[4:7], v[52:55], v[80:83]
	v_mfma_f32_16x16x32_bf16 v[84:87], v[12:15], v[52:55], v[84:87]
	v_mfma_f32_16x16x32_bf16 v[88:91], v[4:7], v[60:63], v[88:91]
	v_mfma_f32_16x16x32_bf16 v[92:95], v[12:15], v[60:63], v[92:95]
	s_setprio 0
	s_setprio 1
	v_mfma_f32_16x16x32_bf16 v[96:99], v[16:19], v[32:35], 0
	v_mfma_f32_16x16x32_bf16 v[32:35], v[24:27], v[32:35], 0
	v_mfma_f32_16x16x32_bf16 v[96:99], v[20:23], v[36:39], v[96:99]
	v_mfma_f32_16x16x32_bf16 v[32:35], v[28:31], v[36:39], v[32:35]
	v_mfma_f32_16x16x32_bf16 v[36:39], v[16:19], v[40:43], 0
	v_mfma_f32_16x16x32_bf16 v[40:43], v[24:27], v[40:43], 0
	v_mfma_f32_16x16x32_bf16 v[36:39], v[20:23], v[44:47], v[36:39]
	v_mfma_f32_16x16x32_bf16 v[40:43], v[28:31], v[44:47], v[40:43]
	v_mfma_f32_16x16x32_bf16 v[44:47], v[16:19], v[48:51], 0
	v_mfma_f32_16x16x32_bf16 v[48:51], v[24:27], v[48:51], 0
	v_mfma_f32_16x16x32_bf16 v[44:47], v[20:23], v[52:55], v[44:47]
	v_mfma_f32_16x16x32_bf16 v[48:51], v[28:31], v[52:55], v[48:51]
	v_mfma_f32_16x16x32_bf16 v[52:55], v[16:19], v[56:59], 0
	v_mfma_f32_16x16x32_bf16 v[56:59], v[24:27], v[56:59], 0
	v_mfma_f32_16x16x32_bf16 v[52:55], v[20:23], v[60:63], v[52:55]
	v_mfma_f32_16x16x32_bf16 v[56:59], v[28:31], v[60:63], v[56:59]
	s_setprio 0
	s_barrier
	s_add_i32 s75, s67, s53
	v_lshl_add_u64 v[210:211], s[44:45], 0, v[132:133]
	s_add_i32 s35, s75, 0x2000
	v_lshl_add_u64 v[140:141], v[210:211], 0, s[18:19]
	s_mov_b32 m0, s75
	v_lshl_add_u64 v[212:213], s[44:45], 0, v[128:129]
	s_add_u32 s78, s44, 0x10100
	ds_read_b128 v[60:63], v157 offset:16384
	ds_read_b128 v[100:103], v157 offset:17408
	ds_read_b128 v[104:107], v157 offset:18432
	ds_read_b128 v[108:111], v157 offset:19456
	ds_read_b128 v[112:115], v157 offset:20480
	ds_read_b128 v[116:119], v157 offset:21504
	ds_read_b128 v[120:123], v157 offset:22528
	ds_read_b128 v[124:127], v157 offset:23552
	global_load_lds_dwordx4 v[140:141], off
	v_lshl_add_u64 v[140:141], v[212:213], 0, s[18:19]
	s_mov_b32 m0, s35
	s_addc_u32 s79, s45, 0
	s_add_i32 s41, s68, s53
	global_load_lds_dwordx4 v[140:141], off
	v_lshl_add_u64 v[140:141], s[78:79], 0, v[132:133]
	s_mov_b32 m0, s41
	s_add_i32 s74, s41, 0x2000
	global_load_lds_dwordx4 v[140:141], off
	v_lshl_add_u64 v[140:141], s[78:79], 0, v[128:129]
	s_mov_b32 m0, s74
	v_lshl_add_u64 v[214:215], s[42:43], 0, v[134:135]
	global_load_lds_dwordx4 v[140:141], off
	v_lshl_add_u64 v[140:141], v[214:215], 0, s[18:19]
	s_mov_b32 m0, s60
	v_lshl_add_u64 v[216:217], s[42:43], 0, v[130:131]
	global_load_lds_dwordx4 v[140:141], off
	v_lshl_add_u64 v[140:141], v[216:217], 0, s[18:19]
	s_mov_b32 m0, s61
	s_nop 0
	global_load_lds_dwordx4 v[140:141], off
	s_waitcnt vmcnt(8)
	s_waitcnt lgkmcnt(0)
	s_barrier
	s_setprio 1
	v_mfma_f32_16x16x32_bf16 v[140:143], v[0:3], v[60:63], 0
	v_mfma_f32_16x16x32_bf16 v[148:151], v[0:3], v[104:107], 0
	v_mfma_f32_16x16x32_bf16 v[162:165], v[0:3], v[112:115], 0
	v_mfma_f32_16x16x32_bf16 v[0:3], v[0:3], v[120:123], 0
	v_mfma_f32_16x16x32_bf16 v[140:143], v[4:7], v[100:103], v[140:143]
	v_mfma_f32_16x16x32_bf16 v[148:151], v[4:7], v[108:111], v[148:151]
	v_mfma_f32_16x16x32_bf16 v[162:165], v[4:7], v[116:119], v[162:165]
	v_mfma_f32_16x16x32_bf16 v[0:3], v[4:7], v[124:127], v[0:3]
	v_mfma_f32_16x16x32_bf16 v[4:7], v[8:11], v[120:123], 0
	v_mfma_f32_16x16x32_bf16 v[144:147], v[8:11], v[60:63], 0
	v_mfma_f32_16x16x32_bf16 v[158:161], v[8:11], v[104:107], 0
	v_mfma_f32_16x16x32_bf16 v[166:169], v[8:11], v[112:115], 0
	v_mfma_f32_16x16x32_bf16 v[4:7], v[12:15], v[124:127], v[4:7]
	v_mfma_f32_16x16x32_bf16 v[144:147], v[12:15], v[100:103], v[144:147]
	v_mfma_f32_16x16x32_bf16 v[158:161], v[12:15], v[108:111], v[158:161]
	v_mfma_f32_16x16x32_bf16 v[166:169], v[12:15], v[116:119], v[166:169]
	s_setprio 0
	s_setprio 1
	v_mfma_f32_16x16x32_bf16 v[8:11], v[16:19], v[60:63], 0
	v_mfma_f32_16x16x32_bf16 v[12:15], v[24:27], v[60:63], 0
	v_mfma_f32_16x16x32_bf16 v[8:11], v[20:23], v[100:103], v[8:11]
	v_mfma_f32_16x16x32_bf16 v[12:15], v[28:31], v[100:103], v[12:15]
	v_mfma_f32_16x16x32_bf16 v[60:63], v[16:19], v[104:107], 0
	v_mfma_f32_16x16x32_bf16 v[100:103], v[24:27], v[104:107], 0
	v_mfma_f32_16x16x32_bf16 v[104:107], v[16:19], v[112:115], 0
	v_mfma_f32_16x16x32_bf16 v[16:19], v[16:19], v[120:123], 0
	v_mfma_f32_16x16x32_bf16 v[60:63], v[20:23], v[108:111], v[60:63]
	v_mfma_f32_16x16x32_bf16 v[100:103], v[28:31], v[108:111], v[100:103]
	v_mfma_f32_16x16x32_bf16 v[104:107], v[20:23], v[116:119], v[104:107]
	v_mfma_f32_16x16x32_bf16 v[108:111], v[24:27], v[112:115], 0
	v_mfma_f32_16x16x32_bf16 v[16:19], v[20:23], v[124:127], v[16:19]
	v_mfma_f32_16x16x32_bf16 v[20:23], v[24:27], v[120:123], 0
	v_mfma_f32_16x16x32_bf16 v[108:111], v[28:31], v[116:119], v[108:111]
	v_mfma_f32_16x16x32_bf16 v[20:23], v[28:31], v[124:127], v[20:23]
	s_setprio 0
	s_barrier
	s_add_i32 s76, 0, 0x18000
	s_add_i32 s82, 0, 0x1c000
	v_add_u32_e32 v136, s76, v153
	v_add_u32_e32 v226, s82, v153
	ds_read_b128 v[24:27], v136
	ds_read_b128 v[28:31], v136 offset:1024
	ds_read_b128 v[112:115], v136 offset:2048
	ds_read_b128 v[116:119], v136 offset:3072
	ds_read_b128 v[120:123], v226
	ds_read_b128 v[124:127], v226 offset:1024
	ds_read_b128 v[170:173], v226 offset:2048
	ds_read_b128 v[174:177], v226 offset:3072
	s_add_u32 s78, s42, 0x40100
	s_addc_u32 s79, s43, 0
	s_mov_b32 m0, s62
	v_lshl_add_u64 v[218:219], s[78:79], 0, v[134:135]
	ds_read_b128 v[178:181], v157 offset:32768
	ds_read_b128 v[182:185], v157 offset:33792
	ds_read_b128 v[186:189], v157 offset:34816
	ds_read_b128 v[190:193], v157 offset:35840
	ds_read_b128 v[194:197], v157 offset:36864
	ds_read_b128 v[198:201], v157 offset:37888
	ds_read_b128 v[202:205], v157 offset:38912
	ds_read_b128 v[206:209], v157 offset:39936
	global_load_lds_dwordx4 v[218:219], off
	v_lshl_add_u64 v[218:219], s[78:79], 0, v[130:131]
	s_mov_b32 m0, s63
	s_nop 0
	global_load_lds_dwordx4 v[218:219], off
	s_waitcnt vmcnt(8)
	s_waitcnt lgkmcnt(0)
	s_barrier
	s_setprio 1
	v_mfma_f32_16x16x32_bf16 v[64:67], v[24:27], v[178:181], v[64:67]
	v_mfma_f32_16x16x32_bf16 v[68:71], v[112:115], v[178:181], v[68:71]
	v_mfma_f32_16x16x32_bf16 v[72:75], v[24:27], v[186:189], v[72:75]
	v_mfma_f32_16x16x32_bf16 v[76:79], v[112:115], v[186:189], v[76:79]
	v_mfma_f32_16x16x32_bf16 v[80:83], v[24:27], v[194:197], v[80:83]
	v_mfma_f32_16x16x32_bf16 v[84:87], v[112:115], v[194:197], v[84:87]
	v_mfma_f32_16x16x32_bf16 v[88:91], v[24:27], v[202:205], v[88:91]
	v_mfma_f32_16x16x32_bf16 v[92:95], v[112:115], v[202:205], v[92:95]
	v_mfma_f32_16x16x32_bf16 v[64:67], v[28:31], v[182:185], v[64:67]
	v_mfma_f32_16x16x32_bf16 v[68:71], v[116:119], v[182:185], v[68:71]
	v_mfma_f32_16x16x32_bf16 v[72:75], v[28:31], v[190:193], v[72:75]
	v_mfma_f32_16x16x32_bf16 v[76:79], v[116:119], v[190:193], v[76:79]
	v_mfma_f32_16x16x32_bf16 v[80:83], v[28:31], v[198:201], v[80:83]
	v_mfma_f32_16x16x32_bf16 v[84:87], v[116:119], v[198:201], v[84:87]
	v_mfma_f32_16x16x32_bf16 v[88:91], v[28:31], v[206:209], v[88:91]
	v_mfma_f32_16x16x32_bf16 v[92:95], v[116:119], v[206:209], v[92:95]
	s_setprio 0
	s_setprio 1
	v_mfma_f32_16x16x32_bf16 v[96:99], v[120:123], v[178:181], v[96:99]
	v_mfma_f32_16x16x32_bf16 v[32:35], v[170:173], v[178:181], v[32:35]
	v_mfma_f32_16x16x32_bf16 v[36:39], v[120:123], v[186:189], v[36:39]
	v_mfma_f32_16x16x32_bf16 v[40:43], v[170:173], v[186:189], v[40:43]
	v_mfma_f32_16x16x32_bf16 v[44:47], v[120:123], v[194:197], v[44:47]
	v_mfma_f32_16x16x32_bf16 v[48:51], v[170:173], v[194:197], v[48:51]
	v_mfma_f32_16x16x32_bf16 v[52:55], v[120:123], v[202:205], v[52:55]
	v_mfma_f32_16x16x32_bf16 v[56:59], v[170:173], v[202:205], v[56:59]
	v_mfma_f32_16x16x32_bf16 v[96:99], v[124:127], v[182:185], v[96:99]
	v_mfma_f32_16x16x32_bf16 v[32:35], v[174:177], v[182:185], v[32:35]
	v_mfma_f32_16x16x32_bf16 v[36:39], v[124:127], v[190:193], v[36:39]
	v_mfma_f32_16x16x32_bf16 v[40:43], v[174:177], v[190:193], v[40:43]
	v_mfma_f32_16x16x32_bf16 v[44:47], v[124:127], v[198:201], v[44:47]
	v_mfma_f32_16x16x32_bf16 v[48:51], v[174:177], v[198:201], v[48:51]
	v_mfma_f32_16x16x32_bf16 v[52:55], v[124:127], v[206:209], v[52:55]
	v_mfma_f32_16x16x32_bf16 v[56:59], v[174:177], v[206:209], v[56:59]
	s_setprio 0
	s_barrier
	s_add_i32 s78, s76, s53
	s_add_i32 s76, s78, 0x2000
	v_lshl_add_u64 v[210:211], v[210:211], 0, s[20:21]
	s_mov_b32 m0, s78
	s_add_u32 s80, s44, 0x10180
	ds_read_b128 v[178:181], v157 offset:49152
	ds_read_b128 v[182:185], v157 offset:50176
	ds_read_b128 v[186:189], v157 offset:51200
	ds_read_b128 v[190:193], v157 offset:52224
	ds_read_b128 v[194:197], v157 offset:53248
	ds_read_b128 v[198:201], v157 offset:54272
	ds_read_b128 v[202:205], v157 offset:55296
	ds_read_b128 v[206:209], v157 offset:56320
	global_load_lds_dwordx4 v[210:211], off
	v_lshl_add_u64 v[210:211], v[212:213], 0, s[20:21]
	s_mov_b32 m0, s76
	s_addc_u32 s81, s45, 0
	s_add_i32 s44, s82, s53
	global_load_lds_dwordx4 v[210:211], off
	v_lshl_add_u64 v[210:211], s[80:81], 0, v[132:133]
	s_mov_b32 m0, s44
	s_add_i32 s45, s44, 0x2000
	global_load_lds_dwordx4 v[210:211], off
	v_lshl_add_u64 v[210:211], s[80:81], 0, v[128:129]
	s_mov_b32 m0, s45
	s_nop 0
	global_load_lds_dwordx4 v[210:211], off
	v_lshl_add_u64 v[210:211], v[214:215], 0, s[20:21]
	s_mov_b32 m0, s64
	s_nop 0
	global_load_lds_dwordx4 v[210:211], off
	v_lshl_add_u64 v[210:211], v[216:217], 0, s[20:21]
	s_mov_b32 m0, s65
	s_nop 0
	global_load_lds_dwordx4 v[210:211], off
	s_waitcnt vmcnt(8)
	s_waitcnt lgkmcnt(0)
	s_barrier
	s_setprio 1
	v_mfma_f32_16x16x32_bf16 v[0:3], v[24:27], v[202:205], v[0:3]
	v_mfma_f32_16x16x32_bf16 v[4:7], v[112:115], v[202:205], v[4:7]
	v_mfma_f32_16x16x32_bf16 v[140:143], v[24:27], v[178:181], v[140:143]
	v_mfma_f32_16x16x32_bf16 v[144:147], v[112:115], v[178:181], v[144:147]
	v_mfma_f32_16x16x32_bf16 v[148:151], v[24:27], v[186:189], v[148:151]
	v_mfma_f32_16x16x32_bf16 v[158:161], v[112:115], v[186:189], v[158:161]
	v_mfma_f32_16x16x32_bf16 v[162:165], v[24:27], v[194:197], v[162:165]
	v_mfma_f32_16x16x32_bf16 v[166:169], v[112:115], v[194:197], v[166:169]
	v_mfma_f32_16x16x32_bf16 v[0:3], v[28:31], v[206:209], v[0:3]
	v_mfma_f32_16x16x32_bf16 v[4:7], v[116:119], v[206:209], v[4:7]
	v_mfma_f32_16x16x32_bf16 v[140:143], v[28:31], v[182:185], v[140:143]
	v_mfma_f32_16x16x32_bf16 v[144:147], v[116:119], v[182:185], v[144:147]
	v_mfma_f32_16x16x32_bf16 v[148:151], v[28:31], v[190:193], v[148:151]
	v_mfma_f32_16x16x32_bf16 v[158:161], v[116:119], v[190:193], v[158:161]
	v_mfma_f32_16x16x32_bf16 v[162:165], v[28:31], v[198:201], v[162:165]
	v_mfma_f32_16x16x32_bf16 v[166:169], v[116:119], v[198:201], v[166:169]
	s_setprio 0
	s_setprio 1
	v_mfma_f32_16x16x32_bf16 v[8:11], v[120:123], v[178:181], v[8:11]
	v_mfma_f32_16x16x32_bf16 v[12:15], v[170:173], v[178:181], v[12:15]
	v_mfma_f32_16x16x32_bf16 v[24:27], v[120:123], v[186:189], v[60:63]
	v_mfma_f32_16x16x32_bf16 v[28:31], v[170:173], v[186:189], v[100:103]
	v_mfma_f32_16x16x32_bf16 v[60:63], v[120:123], v[194:197], v[104:107]
	v_mfma_f32_16x16x32_bf16 v[100:103], v[170:173], v[194:197], v[108:111]
	v_mfma_f32_16x16x32_bf16 v[16:19], v[120:123], v[202:205], v[16:19]
	v_mfma_f32_16x16x32_bf16 v[20:23], v[170:173], v[202:205], v[20:23]
	v_mfma_f32_16x16x32_bf16 v[8:11], v[124:127], v[182:185], v[8:11]
	v_mfma_f32_16x16x32_bf16 v[12:15], v[174:177], v[182:185], v[12:15]
	v_mfma_f32_16x16x32_bf16 v[24:27], v[124:127], v[190:193], v[24:27]
	v_mfma_f32_16x16x32_bf16 v[28:31], v[174:177], v[190:193], v[28:31]
	v_mfma_f32_16x16x32_bf16 v[60:63], v[124:127], v[198:201], v[60:63]
	v_mfma_f32_16x16x32_bf16 v[100:103], v[174:177], v[198:201], v[100:103]
	v_mfma_f32_16x16x32_bf16 v[16:19], v[124:127], v[206:209], v[16:19]
	v_mfma_f32_16x16x32_bf16 v[20:23], v[174:177], v[206:209], v[20:23]
	s_setprio 0
	s_barrier
	ds_read_b128 v[104:107], v155
	ds_read_b128 v[108:111], v155 offset:1024
	ds_read_b128 v[112:115], v155 offset:2048
	ds_read_b128 v[116:119], v155 offset:3072
	ds_read_b128 v[120:123], v156
	ds_read_b128 v[124:127], v156 offset:1024
	ds_read_b128 v[170:173], v156 offset:2048
	ds_read_b128 v[174:177], v156 offset:3072
	s_add_u32 s42, s42, 0x40180
	s_addc_u32 s43, s43, 0
	s_mov_b32 m0, s77
	v_lshl_add_u64 v[210:211], s[42:43], 0, v[134:135]
	ds_read_b128 v[178:181], v157
	ds_read_b128 v[182:185], v157 offset:1024
	ds_read_b128 v[186:189], v157 offset:2048
	ds_read_b128 v[190:193], v157 offset:3072
	ds_read_b128 v[194:197], v157 offset:4096
	ds_read_b128 v[198:201], v157 offset:5120
	ds_read_b128 v[202:205], v157 offset:6144
	ds_read_b128 v[206:209], v157 offset:7168
	global_load_lds_dwordx4 v[210:211], off
	v_lshl_add_u64 v[210:211], s[42:43], 0, v[130:131]
	s_mov_b32 m0, s31
	s_nop 0
	global_load_lds_dwordx4 v[210:211], off
	s_waitcnt vmcnt(8)
	s_waitcnt lgkmcnt(0)
	s_barrier
	s_setprio 1
	v_mfma_f32_16x16x32_bf16 v[64:67], v[104:107], v[178:181], v[64:67]
	v_mfma_f32_16x16x32_bf16 v[68:71], v[112:115], v[178:181], v[68:71]
	v_mfma_f32_16x16x32_bf16 v[72:75], v[104:107], v[186:189], v[72:75]
	v_mfma_f32_16x16x32_bf16 v[76:79], v[112:115], v[186:189], v[76:79]
	v_mfma_f32_16x16x32_bf16 v[80:83], v[104:107], v[194:197], v[80:83]
	v_mfma_f32_16x16x32_bf16 v[84:87], v[112:115], v[194:197], v[84:87]
	v_mfma_f32_16x16x32_bf16 v[88:91], v[104:107], v[202:205], v[88:91]
	v_mfma_f32_16x16x32_bf16 v[92:95], v[112:115], v[202:205], v[92:95]
	v_mfma_f32_16x16x32_bf16 v[64:67], v[108:111], v[182:185], v[64:67]
	v_mfma_f32_16x16x32_bf16 v[68:71], v[116:119], v[182:185], v[68:71]
	v_mfma_f32_16x16x32_bf16 v[72:75], v[108:111], v[190:193], v[72:75]
	v_mfma_f32_16x16x32_bf16 v[76:79], v[116:119], v[190:193], v[76:79]
	v_mfma_f32_16x16x32_bf16 v[80:83], v[108:111], v[198:201], v[80:83]
	v_mfma_f32_16x16x32_bf16 v[84:87], v[116:119], v[198:201], v[84:87]
	v_mfma_f32_16x16x32_bf16 v[88:91], v[108:111], v[206:209], v[88:91]
	v_mfma_f32_16x16x32_bf16 v[92:95], v[116:119], v[206:209], v[92:95]
	s_setprio 0
	s_setprio 1
	v_mfma_f32_16x16x32_bf16 v[32:35], v[170:173], v[178:181], v[32:35]
	v_mfma_f32_16x16x32_bf16 v[96:99], v[120:123], v[178:181], v[96:99]
	v_mfma_f32_16x16x32_bf16 v[178:181], v[174:177], v[182:185], v[32:35]
	v_mfma_f32_16x16x32_bf16 v[32:35], v[120:123], v[186:189], v[36:39]
	v_mfma_f32_16x16x32_bf16 v[96:99], v[124:127], v[182:185], v[96:99]
	v_mfma_f32_16x16x32_bf16 v[182:185], v[124:127], v[190:193], v[32:35]
	v_mfma_f32_16x16x32_bf16 v[32:35], v[170:173], v[186:189], v[40:43]
	v_mfma_f32_16x16x32_bf16 v[40:43], v[174:177], v[190:193], v[32:35]
	v_mfma_f32_16x16x32_bf16 v[32:35], v[120:123], v[194:197], v[44:47]
	v_mfma_f32_16x16x32_bf16 v[44:47], v[124:127], v[198:201], v[32:35]
	v_mfma_f32_16x16x32_bf16 v[32:35], v[170:173], v[194:197], v[48:51]
	v_mfma_f32_16x16x32_bf16 v[186:189], v[174:177], v[198:201], v[32:35]
	v_mfma_f32_16x16x32_bf16 v[32:35], v[120:123], v[202:205], v[52:55]
	v_mfma_f32_16x16x32_bf16 v[52:55], v[124:127], v[206:209], v[32:35]
	v_mfma_f32_16x16x32_bf16 v[32:35], v[170:173], v[202:205], v[56:59]
	v_mfma_f32_16x16x32_bf16 v[190:193], v[174:177], v[206:209], v[32:35]
	s_setprio 0
	s_barrier
	s_mov_b32 m0, s75
	v_lshl_add_u64 v[246:247], s[46:47], 0, v[132:133]
	s_add_u32 s42, s46, 0x10000
	s_nop 1
	ds_read_b128 v[32:35], v157 offset:16384
	ds_read_b128 v[36:39], v157 offset:17408
	ds_read_b128 v[48:51], v157 offset:18432
	ds_read_b128 v[56:59], v157 offset:19456
	ds_read_b128 v[194:197], v157 offset:20480
	ds_read_b128 v[198:201], v157 offset:21504
	ds_read_b128 v[202:205], v157 offset:22528
	ds_read_b128 v[206:209], v157 offset:23552
	global_load_lds_dwordx4 v[246:247], off
	v_lshl_add_u64 v[248:249], s[46:47], 0, v[128:129]
	s_mov_b32 m0, s35
	s_addc_u32 s43, s47, 0
	global_load_lds_dwordx4 v[248:249], off
	v_lshl_add_u64 v[210:211], s[42:43], 0, v[132:133]
	s_mov_b32 m0, s41
	v_lshl_add_u64 v[250:251], s[48:49], 0, v[134:135]
	global_load_lds_dwordx4 v[210:211], off
	v_lshl_add_u64 v[210:211], s[42:43], 0, v[128:129]
	s_mov_b32 m0, s74
	v_lshl_add_u64 v[252:253], s[48:49], 0, v[130:131]
	global_load_lds_dwordx4 v[210:211], off
	s_mov_b32 m0, s60
	s_nop 0
	global_load_lds_dwordx4 v[250:251], off
	s_mov_b32 m0, s61
	s_nop 0
	global_load_lds_dwordx4 v[252:253], off
	s_waitcnt vmcnt(8)
	s_waitcnt lgkmcnt(0)
	s_barrier
	s_setprio 1
	v_mfma_f32_16x16x32_bf16 v[0:3], v[104:107], v[202:205], v[0:3]
	v_mfma_f32_16x16x32_bf16 v[140:143], v[104:107], v[32:35], v[140:143]
	v_mfma_f32_16x16x32_bf16 v[148:151], v[104:107], v[48:51], v[148:151]
	v_mfma_f32_16x16x32_bf16 v[162:165], v[104:107], v[194:197], v[162:165]
	v_mfma_f32_16x16x32_bf16 v[104:107], v[108:111], v[206:209], v[0:3]
	v_mfma_f32_16x16x32_bf16 v[0:3], v[112:115], v[202:205], v[4:7]
	v_mfma_f32_16x16x32_bf16 v[140:143], v[108:111], v[36:39], v[140:143]
	v_mfma_f32_16x16x32_bf16 v[144:147], v[112:115], v[32:35], v[144:147]
	v_mfma_f32_16x16x32_bf16 v[148:151], v[108:111], v[56:59], v[148:151]
	v_mfma_f32_16x16x32_bf16 v[158:161], v[112:115], v[48:51], v[158:161]
	v_mfma_f32_16x16x32_bf16 v[162:165], v[108:111], v[198:201], v[162:165]
	v_mfma_f32_16x16x32_bf16 v[166:169], v[112:115], v[194:197], v[166:169]
	v_mfma_f32_16x16x32_bf16 v[108:111], v[116:119], v[206:209], v[0:3]
	v_mfma_f32_16x16x32_bf16 v[144:147], v[116:119], v[36:39], v[144:147]
	v_mfma_f32_16x16x32_bf16 v[158:161], v[116:119], v[56:59], v[158:161]
	v_mfma_f32_16x16x32_bf16 v[166:169], v[116:119], v[198:201], v[166:169]
	s_setprio 0
	s_setprio 1
	v_mfma_f32_16x16x32_bf16 v[0:3], v[120:123], v[32:35], v[8:11]
	v_mfma_f32_16x16x32_bf16 v[112:115], v[124:127], v[36:39], v[0:3]
	v_mfma_f32_16x16x32_bf16 v[0:3], v[170:173], v[32:35], v[12:15]
	v_mfma_f32_16x16x32_bf16 v[116:119], v[174:177], v[36:39], v[0:3]
	v_mfma_f32_16x16x32_bf16 v[0:3], v[120:123], v[48:51], v[24:27]
	v_mfma_f32_16x16x32_bf16 v[210:213], v[124:127], v[56:59], v[0:3]
	v_mfma_f32_16x16x32_bf16 v[0:3], v[170:173], v[48:51], v[28:31]
	v_mfma_f32_16x16x32_bf16 v[214:217], v[174:177], v[56:59], v[0:3]
	v_mfma_f32_16x16x32_bf16 v[0:3], v[120:123], v[194:197], v[60:63]
	v_mfma_f32_16x16x32_bf16 v[218:221], v[124:127], v[198:201], v[0:3]
	v_mfma_f32_16x16x32_bf16 v[0:3], v[170:173], v[194:197], v[100:103]
	v_mfma_f32_16x16x32_bf16 v[194:197], v[174:177], v[198:201], v[0:3]
	v_mfma_f32_16x16x32_bf16 v[0:3], v[120:123], v[202:205], v[16:19]
	v_mfma_f32_16x16x32_bf16 v[198:201], v[124:127], v[206:209], v[0:3]
	v_mfma_f32_16x16x32_bf16 v[0:3], v[170:173], v[202:205], v[20:23]
	v_mfma_f32_16x16x32_bf16 v[170:173], v[174:177], v[206:209], v[0:3]
	s_setprio 0
	s_barrier
	ds_read_b128 v[60:63], v136
	ds_read_b128 v[120:123], v136 offset:1024
	ds_read_b128 v[124:127], v136 offset:2048
	ds_read_b128 v[174:177], v136 offset:3072
	ds_read_b128 v[202:205], v226
	ds_read_b128 v[206:209], v226 offset:1024
	ds_read_b128 v[222:225], v226 offset:2048
	ds_read_b128 v[226:229], v226 offset:3072
	s_add_u32 s42, s48, 0x40000
	s_addc_u32 s43, s49, 0
	s_mov_b32 m0, s62
	v_lshl_add_u64 v[0:1], s[42:43], 0, v[134:135]
	ds_read_b128 v[24:27], v157 offset:32768
	ds_read_b128 v[28:31], v157 offset:33792
	ds_read_b128 v[56:59], v157 offset:34816
	ds_read_b128 v[100:103], v157 offset:35840
	ds_read_b128 v[230:233], v157 offset:36864
	ds_read_b128 v[234:237], v157 offset:37888
	ds_read_b128 v[238:241], v157 offset:38912
	ds_read_b128 v[242:245], v157 offset:39936
	global_load_lds_dwordx4 v[0:1], off
	v_lshl_add_u64 v[0:1], s[42:43], 0, v[130:131]
	s_mov_b32 m0, s63
	s_nop 0
	global_load_lds_dwordx4 v[0:1], off
	s_waitcnt vmcnt(8)
	s_waitcnt lgkmcnt(0)
	s_barrier
	s_setprio 1
	v_mfma_f32_16x16x32_bf16 v[0:3], v[60:63], v[24:27], v[64:67]
	v_mfma_f32_16x16x32_bf16 v[32:35], v[120:123], v[28:31], v[0:3]
	v_mfma_f32_16x16x32_bf16 v[0:3], v[124:127], v[24:27], v[68:71]
	v_mfma_f32_16x16x32_bf16 v[36:39], v[174:177], v[28:31], v[0:3]
	v_mfma_f32_16x16x32_bf16 v[0:3], v[60:63], v[56:59], v[72:75]
	v_mfma_f32_16x16x32_bf16 v[16:19], v[120:123], v[100:103], v[0:3]
	v_mfma_f32_16x16x32_bf16 v[0:3], v[124:127], v[56:59], v[76:79]
	v_mfma_f32_16x16x32_bf16 v[20:23], v[174:177], v[100:103], v[0:3]
	v_mfma_f32_16x16x32_bf16 v[0:3], v[60:63], v[230:233], v[80:83]
	v_mfma_f32_16x16x32_bf16 v[8:11], v[120:123], v[234:237], v[0:3]
	v_mfma_f32_16x16x32_bf16 v[0:3], v[124:127], v[230:233], v[84:87]
	v_mfma_f32_16x16x32_bf16 v[12:15], v[174:177], v[234:237], v[0:3]
	v_mfma_f32_16x16x32_bf16 v[0:3], v[60:63], v[238:241], v[88:91]
	v_mfma_f32_16x16x32_bf16 v[4:7], v[124:127], v[238:241], v[92:95]
	v_mfma_f32_16x16x32_bf16 v[0:3], v[120:123], v[242:245], v[0:3]
	v_mfma_f32_16x16x32_bf16 v[4:7], v[174:177], v[242:245], v[4:7]
	s_setprio 0
	s_setprio 1
	v_mfma_f32_16x16x32_bf16 v[48:51], v[202:205], v[24:27], v[96:99]
	v_mfma_f32_16x16x32_bf16 v[24:27], v[222:225], v[24:27], v[178:181]
	v_mfma_f32_16x16x32_bf16 v[72:75], v[226:229], v[28:31], v[24:27]
	v_mfma_f32_16x16x32_bf16 v[24:27], v[202:205], v[56:59], v[182:185]
	v_mfma_f32_16x16x32_bf16 v[64:67], v[206:209], v[28:31], v[48:51]
	v_mfma_f32_16x16x32_bf16 v[48:51], v[206:209], v[100:103], v[24:27]
	v_mfma_f32_16x16x32_bf16 v[24:27], v[222:225], v[56:59], v[40:43]
	v_mfma_f32_16x16x32_bf16 v[56:59], v[226:229], v[100:103], v[24:27]
	v_mfma_f32_16x16x32_bf16 v[24:27], v[202:205], v[230:233], v[44:47]
	v_mfma_f32_16x16x32_bf16 v[40:43], v[206:209], v[234:237], v[24:27]
	v_mfma_f32_16x16x32_bf16 v[24:27], v[222:225], v[230:233], v[186:189]
	v_mfma_f32_16x16x32_bf16 v[44:47], v[226:229], v[234:237], v[24:27]
	v_mfma_f32_16x16x32_bf16 v[24:27], v[202:205], v[238:241], v[52:55]
	v_mfma_f32_16x16x32_bf16 v[28:31], v[222:225], v[238:241], v[190:193]
	v_mfma_f32_16x16x32_bf16 v[24:27], v[206:209], v[242:245], v[24:27]
	v_mfma_f32_16x16x32_bf16 v[28:31], v[226:229], v[242:245], v[28:31]
	s_setprio 0
	s_barrier
	s_mov_b32 m0, s78
	v_lshl_add_u64 v[52:53], v[246:247], 0, s[12:13]
	s_add_u32 s42, s46, 0x10080
	ds_read_b128 v[88:91], v157 offset:49152
	ds_read_b128 v[92:95], v157 offset:50176
	ds_read_b128 v[178:181], v157 offset:51200
	ds_read_b128 v[182:185], v157 offset:52224
	ds_read_b128 v[186:189], v157 offset:53248
	ds_read_b128 v[190:193], v157 offset:54272
	ds_read_b128 v[230:233], v157 offset:55296
	ds_read_b128 v[234:237], v157 offset:56320
	global_load_lds_dwordx4 v[52:53], off
	v_lshl_add_u64 v[52:53], v[248:249], 0, s[12:13]
	s_mov_b32 m0, s76
	s_addc_u32 s43, s47, 0
	global_load_lds_dwordx4 v[52:53], off
	v_lshl_add_u64 v[52:53], s[42:43], 0, v[132:133]
	s_mov_b32 m0, s44
	s_nop 0
	global_load_lds_dwordx4 v[52:53], off
	v_lshl_add_u64 v[52:53], s[42:43], 0, v[128:129]
	s_mov_b32 m0, s45
	s_nop 0
	global_load_lds_dwordx4 v[52:53], off
	v_lshl_add_u64 v[52:53], v[250:251], 0, s[12:13]
	s_mov_b32 m0, s64
	s_nop 0
	global_load_lds_dwordx4 v[52:53], off
	v_lshl_add_u64 v[52:53], v[252:253], 0, s[12:13]
	s_mov_b32 m0, s65
	s_nop 0
	global_load_lds_dwordx4 v[52:53], off
	s_waitcnt vmcnt(8)
	s_waitcnt lgkmcnt(0)
	s_barrier
	s_setprio 1
	v_mfma_f32_16x16x32_bf16 v[52:55], v[60:63], v[88:91], v[140:143]
	v_mfma_f32_16x16x32_bf16 v[96:99], v[120:123], v[92:95], v[52:55]
	v_mfma_f32_16x16x32_bf16 v[52:55], v[124:127], v[88:91], v[144:147]
	v_mfma_f32_16x16x32_bf16 v[100:103], v[174:177], v[92:95], v[52:55]
	v_mfma_f32_16x16x32_bf16 v[52:55], v[60:63], v[178:181], v[148:151]
	v_mfma_f32_16x16x32_bf16 v[80:83], v[120:123], v[182:185], v[52:55]
	v_mfma_f32_16x16x32_bf16 v[52:55], v[124:127], v[178:181], v[158:161]
	v_mfma_f32_16x16x32_bf16 v[84:87], v[174:177], v[182:185], v[52:55]
	v_mfma_f32_16x16x32_bf16 v[52:55], v[60:63], v[186:189], v[162:165]
	v_mfma_f32_16x16x32_bf16 v[68:71], v[120:123], v[190:193], v[52:55]
	v_mfma_f32_16x16x32_bf16 v[52:55], v[124:127], v[186:189], v[166:169]
	v_mfma_f32_16x16x32_bf16 v[76:79], v[174:177], v[190:193], v[52:55]
	v_mfma_f32_16x16x32_bf16 v[52:55], v[60:63], v[230:233], v[104:107]
	v_mfma_f32_16x16x32_bf16 v[60:63], v[124:127], v[230:233], v[108:111]
	v_mfma_f32_16x16x32_bf16 v[52:55], v[120:123], v[234:237], v[52:55]
	v_mfma_f32_16x16x32_bf16 v[60:63], v[174:177], v[234:237], v[60:63]
	s_setprio 0
	s_setprio 1
	v_mfma_f32_16x16x32_bf16 v[104:107], v[202:205], v[88:91], v[112:115]
	v_mfma_f32_16x16x32_bf16 v[88:91], v[222:225], v[88:91], v[116:119]
	v_mfma_f32_16x16x32_bf16 v[124:127], v[226:229], v[92:95], v[88:91]
	v_mfma_f32_16x16x32_bf16 v[88:91], v[202:205], v[178:181], v[210:213]
	v_mfma_f32_16x16x32_bf16 v[112:115], v[206:209], v[182:185], v[88:91]
	v_mfma_f32_16x16x32_bf16 v[88:91], v[222:225], v[178:181], v[214:217]
	v_mfma_f32_16x16x32_bf16 v[116:119], v[226:229], v[182:185], v[88:91]
	v_mfma_f32_16x16x32_bf16 v[88:91], v[202:205], v[186:189], v[218:221]
	v_mfma_f32_16x16x32_bf16 v[120:123], v[206:209], v[92:95], v[104:107]
	v_mfma_f32_16x16x32_bf16 v[104:107], v[206:209], v[190:193], v[88:91]
	v_mfma_f32_16x16x32_bf16 v[88:91], v[222:225], v[186:189], v[194:197]
	v_mfma_f32_16x16x32_bf16 v[108:111], v[226:229], v[190:193], v[88:91]
	v_mfma_f32_16x16x32_bf16 v[88:91], v[202:205], v[230:233], v[198:201]
	v_mfma_f32_16x16x32_bf16 v[92:95], v[222:225], v[230:233], v[170:173]
	v_mfma_f32_16x16x32_bf16 v[88:91], v[206:209], v[234:237], v[88:91]
	v_mfma_f32_16x16x32_bf16 v[92:95], v[226:229], v[234:237], v[92:95]
	s_setprio 0
	s_barrier
	s_andn2_b64 vcc, exec, s[14:15]
	s_cbranch_vccnz .LBB0_620
	s_barrier

.LBB0_1363:
	ds_read_b128 v[144:147], v151
	ds_read_b128 v[154:157], v151 offset:1024
	ds_read_b128 v[158:161], v151 offset:2048
	ds_read_b128 v[162:165], v151 offset:3072
	ds_read_b128 v[166:169], v152
	ds_read_b128 v[170:173], v152 offset:1024
	ds_read_b128 v[174:177], v152 offset:2048
	ds_read_b128 v[178:181], v152 offset:3072
	s_add_u32 s34, s30, 0xfff00080
	s_addc_u32 s35, s31, -1
	s_cmp_eq_u32 s56, 60
	s_cselect_b32 s37, s0, s35
	s_cselect_b32 s36, s1, s34
	s_cselect_b32 s35, s19, s55
	s_cselect_b32 s34, s21, s27
	v_lshl_add_u64 v[214:215], s[30:31], 0, v[138:139]
	s_add_i32 m0, s29, 0xc000
	ds_read_b128 v[182:185], v153
	ds_read_b128 v[186:189], v153 offset:1024
	ds_read_b128 v[190:193], v153 offset:2048
	ds_read_b128 v[194:197], v153 offset:3072
	ds_read_b128 v[198:201], v153 offset:4096
	ds_read_b128 v[202:205], v153 offset:5120
	ds_read_b128 v[206:209], v153 offset:6144
	ds_read_b128 v[210:213], v153 offset:7168
	global_load_lds_dwordx4 v[214:215], off
	v_lshl_add_u64 v[214:215], s[30:31], 0, v[136:137]
	s_add_i32 m0, s29, 0xe000
	s_nop 0
	global_load_lds_dwordx4 v[214:215], off
	s_waitcnt vmcnt(8)
	s_waitcnt lgkmcnt(0)
	s_barrier
	s_setprio 1
	v_mfma_f32_16x16x32_bf16 v[124:127], v[144:147], v[182:185], v[124:127]
	v_mfma_f32_16x16x32_bf16 v[120:123], v[158:161], v[182:185], v[120:123]
	v_mfma_f32_16x16x32_bf16 v[108:111], v[144:147], v[190:193], v[108:111]
	v_mfma_f32_16x16x32_bf16 v[104:107], v[158:161], v[190:193], v[104:107]
	v_mfma_f32_16x16x32_bf16 v[92:95], v[144:147], v[198:201], v[92:95]
	v_mfma_f32_16x16x32_bf16 v[88:91], v[158:161], v[198:201], v[88:91]
	v_mfma_f32_16x16x32_bf16 v[76:79], v[144:147], v[206:209], v[76:79]
	v_mfma_f32_16x16x32_bf16 v[72:75], v[158:161], v[206:209], v[72:75]
	v_mfma_f32_16x16x32_bf16 v[124:127], v[154:157], v[186:189], v[124:127]
	v_mfma_f32_16x16x32_bf16 v[120:123], v[162:165], v[186:189], v[120:123]
	v_mfma_f32_16x16x32_bf16 v[108:111], v[154:157], v[194:197], v[108:111]
	v_mfma_f32_16x16x32_bf16 v[104:107], v[162:165], v[194:197], v[104:107]
	v_mfma_f32_16x16x32_bf16 v[92:95], v[154:157], v[202:205], v[92:95]
	v_mfma_f32_16x16x32_bf16 v[88:91], v[162:165], v[202:205], v[88:91]
	v_mfma_f32_16x16x32_bf16 v[76:79], v[154:157], v[210:213], v[76:79]
	v_mfma_f32_16x16x32_bf16 v[72:75], v[162:165], v[210:213], v[72:75]
	s_setprio 0
	s_setprio 1
	v_mfma_f32_16x16x32_bf16 v[116:119], v[166:169], v[182:185], v[116:119]
	v_mfma_f32_16x16x32_bf16 v[112:115], v[174:177], v[182:185], v[112:115]
	v_mfma_f32_16x16x32_bf16 v[100:103], v[166:169], v[190:193], v[100:103]
	v_mfma_f32_16x16x32_bf16 v[96:99], v[174:177], v[190:193], v[96:99]
	v_mfma_f32_16x16x32_bf16 v[84:87], v[166:169], v[198:201], v[84:87]
	v_mfma_f32_16x16x32_bf16 v[80:83], v[174:177], v[198:201], v[80:83]
	v_mfma_f32_16x16x32_bf16 v[68:71], v[166:169], v[206:209], v[68:71]
	v_mfma_f32_16x16x32_bf16 v[64:67], v[174:177], v[206:209], v[64:67]
	v_mfma_f32_16x16x32_bf16 v[116:119], v[170:173], v[186:189], v[116:119]
	v_mfma_f32_16x16x32_bf16 v[112:115], v[178:181], v[186:189], v[112:115]
	v_mfma_f32_16x16x32_bf16 v[100:103], v[170:173], v[194:197], v[100:103]
	v_mfma_f32_16x16x32_bf16 v[96:99], v[178:181], v[194:197], v[96:99]
	v_mfma_f32_16x16x32_bf16 v[84:87], v[170:173], v[202:205], v[84:87]
	v_mfma_f32_16x16x32_bf16 v[80:83], v[178:181], v[202:205], v[80:83]
	v_mfma_f32_16x16x32_bf16 v[68:71], v[170:173], v[210:213], v[68:71]
	v_mfma_f32_16x16x32_bf16 v[64:67], v[178:181], v[210:213], v[64:67]
	s_setprio 0
	s_barrier
	s_add_i32 s57, s53, s44
	v_lshl_add_u64 v[214:215], s[34:35], 0, v[130:131]
	s_mov_b32 m0, s57
	ds_read_b128 v[182:185], v153 offset:16384
	ds_read_b128 v[186:189], v153 offset:17408
	ds_read_b128 v[190:193], v153 offset:18432
	ds_read_b128 v[194:197], v153 offset:19456
	ds_read_b128 v[198:201], v153 offset:20480
	ds_read_b128 v[202:205], v153 offset:21504
	ds_read_b128 v[206:209], v153 offset:22528
	ds_read_b128 v[210:213], v153 offset:23552
	global_load_lds_dwordx4 v[214:215], off
	s_add_i32 m0, s57, 0x2000
	s_add_u32 s58, s34, 0x100000
	v_lshl_add_u64 v[216:217], s[34:35], 0, v[134:135]
	s_addc_u32 s59, s35, 0
	s_add_i32 s57, s54, s44
	global_load_lds_dwordx4 v[216:217], off
	v_lshl_add_u64 v[218:219], s[58:59], 0, v[130:131]
	s_mov_b32 m0, s57
	v_lshl_add_u64 v[220:221], s[36:37], 0, v[132:133]
	global_load_lds_dwordx4 v[218:219], off
	v_lshl_add_u64 v[218:219], s[58:59], 0, v[134:135]
	s_add_i32 m0, s57, 0x2000
	s_nop 0
	global_load_lds_dwordx4 v[218:219], off
	v_lshl_add_u64 v[218:219], s[36:37], 0, v[128:129]
	s_mov_b32 m0, s29
	s_nop 0
	global_load_lds_dwordx4 v[218:219], off
	s_mov_b32 m0, s45
	s_nop 0
	global_load_lds_dwordx4 v[220:221], off
	s_waitcnt vmcnt(8)
	s_waitcnt lgkmcnt(0)
	s_barrier
	s_setprio 1
	v_mfma_f32_16x16x32_bf16 v[60:63], v[144:147], v[182:185], v[60:63]
	v_mfma_f32_16x16x32_bf16 v[56:59], v[158:161], v[182:185], v[56:59]
	v_mfma_f32_16x16x32_bf16 v[44:47], v[144:147], v[190:193], v[44:47]
	v_mfma_f32_16x16x32_bf16 v[40:43], v[158:161], v[190:193], v[40:43]
	v_mfma_f32_16x16x32_bf16 v[28:31], v[144:147], v[198:201], v[28:31]
	v_mfma_f32_16x16x32_bf16 v[24:27], v[158:161], v[198:201], v[24:27]
	v_mfma_f32_16x16x32_bf16 v[12:15], v[144:147], v[206:209], v[12:15]
	v_mfma_f32_16x16x32_bf16 v[8:11], v[158:161], v[206:209], v[8:11]
	v_mfma_f32_16x16x32_bf16 v[60:63], v[154:157], v[186:189], v[60:63]
	v_mfma_f32_16x16x32_bf16 v[56:59], v[162:165], v[186:189], v[56:59]
	v_mfma_f32_16x16x32_bf16 v[44:47], v[154:157], v[194:197], v[44:47]
	v_mfma_f32_16x16x32_bf16 v[40:43], v[162:165], v[194:197], v[40:43]
	v_mfma_f32_16x16x32_bf16 v[28:31], v[154:157], v[202:205], v[28:31]
	v_mfma_f32_16x16x32_bf16 v[24:27], v[162:165], v[202:205], v[24:27]
	v_mfma_f32_16x16x32_bf16 v[12:15], v[154:157], v[210:213], v[12:15]
	v_mfma_f32_16x16x32_bf16 v[8:11], v[162:165], v[210:213], v[8:11]
	s_setprio 0
	s_setprio 1
	v_mfma_f32_16x16x32_bf16 v[52:55], v[166:169], v[182:185], v[52:55]
	v_mfma_f32_16x16x32_bf16 v[48:51], v[174:177], v[182:185], v[48:51]
	v_mfma_f32_16x16x32_bf16 v[36:39], v[166:169], v[190:193], v[36:39]
	v_mfma_f32_16x16x32_bf16 v[32:35], v[174:177], v[190:193], v[32:35]
	v_mfma_f32_16x16x32_bf16 v[20:23], v[166:169], v[198:201], v[20:23]
	v_mfma_f32_16x16x32_bf16 v[16:19], v[174:177], v[198:201], v[16:19]
	v_mfma_f32_16x16x32_bf16 v[4:7], v[166:169], v[206:209], v[4:7]
	v_mfma_f32_16x16x32_bf16 v[0:3], v[174:177], v[206:209], v[0:3]
	v_mfma_f32_16x16x32_bf16 v[52:55], v[170:173], v[186:189], v[52:55]
	v_mfma_f32_16x16x32_bf16 v[48:51], v[178:181], v[186:189], v[48:51]
	v_mfma_f32_16x16x32_bf16 v[36:39], v[170:173], v[194:197], v[36:39]
	v_mfma_f32_16x16x32_bf16 v[32:35], v[178:181], v[194:197], v[32:35]
	v_mfma_f32_16x16x32_bf16 v[20:23], v[170:173], v[202:205], v[20:23]
	v_mfma_f32_16x16x32_bf16 v[16:19], v[178:181], v[202:205], v[16:19]
	v_mfma_f32_16x16x32_bf16 v[4:7], v[170:173], v[210:213], v[4:7]
	v_mfma_f32_16x16x32_bf16 v[0:3], v[178:181], v[210:213], v[0:3]
	s_setprio 0
	s_barrier
	s_add_i32 s57, 0, 0x18000
	s_add_i32 s58, 0, 0x1c000
	v_add_u32_e32 v162, s57, v149
	v_add_u32_e32 v178, s58, v149
	ds_read_b128 v[144:147], v162
	ds_read_b128 v[154:157], v162 offset:1024
	ds_read_b128 v[158:161], v162 offset:2048
	ds_read_b128 v[162:165], v162 offset:3072
	ds_read_b128 v[166:169], v178
	ds_read_b128 v[170:173], v178 offset:1024
	ds_read_b128 v[174:177], v178 offset:2048
	ds_read_b128 v[178:181], v178 offset:3072
	s_add_u32 s36, s36, 0x100000
	s_addc_u32 s37, s37, 0
	s_mov_b32 m0, s46
	v_lshl_add_u64 v[222:223], s[36:37], 0, v[128:129]
	ds_read_b128 v[182:185], v153 offset:32768
	ds_read_b128 v[186:189], v153 offset:33792
	ds_read_b128 v[190:193], v153 offset:34816
	ds_read_b128 v[194:197], v153 offset:35840
	ds_read_b128 v[198:201], v153 offset:36864
	ds_read_b128 v[202:205], v153 offset:37888
	ds_read_b128 v[206:209], v153 offset:38912
	ds_read_b128 v[210:213], v153 offset:39936
	global_load_lds_dwordx4 v[222:223], off
	v_lshl_add_u64 v[222:223], s[36:37], 0, v[132:133]
	s_mov_b32 m0, s47
	s_nop 0
	global_load_lds_dwordx4 v[222:223], off
	s_waitcnt vmcnt(8)
	s_waitcnt lgkmcnt(0)
	s_barrier
	s_setprio 1
	v_mfma_f32_16x16x32_bf16 v[124:127], v[144:147], v[182:185], v[124:127]
	v_mfma_f32_16x16x32_bf16 v[120:123], v[158:161], v[182:185], v[120:123]
	v_mfma_f32_16x16x32_bf16 v[108:111], v[144:147], v[190:193], v[108:111]
	v_mfma_f32_16x16x32_bf16 v[104:107], v[158:161], v[190:193], v[104:107]
	v_mfma_f32_16x16x32_bf16 v[92:95], v[144:147], v[198:201], v[92:95]
	v_mfma_f32_16x16x32_bf16 v[88:91], v[158:161], v[198:201], v[88:91]
	v_mfma_f32_16x16x32_bf16 v[76:79], v[144:147], v[206:209], v[76:79]
	v_mfma_f32_16x16x32_bf16 v[72:75], v[158:161], v[206:209], v[72:75]
	v_mfma_f32_16x16x32_bf16 v[124:127], v[154:157], v[186:189], v[124:127]
	v_mfma_f32_16x16x32_bf16 v[120:123], v[162:165], v[186:189], v[120:123]
	v_mfma_f32_16x16x32_bf16 v[108:111], v[154:157], v[194:197], v[108:111]
	v_mfma_f32_16x16x32_bf16 v[104:107], v[162:165], v[194:197], v[104:107]
	v_mfma_f32_16x16x32_bf16 v[92:95], v[154:157], v[202:205], v[92:95]
	v_mfma_f32_16x16x32_bf16 v[88:91], v[162:165], v[202:205], v[88:91]
	v_mfma_f32_16x16x32_bf16 v[76:79], v[154:157], v[210:213], v[76:79]
	v_mfma_f32_16x16x32_bf16 v[72:75], v[162:165], v[210:213], v[72:75]
	s_setprio 0
	s_setprio 1
	v_mfma_f32_16x16x32_bf16 v[116:119], v[166:169], v[182:185], v[116:119]
	v_mfma_f32_16x16x32_bf16 v[112:115], v[174:177], v[182:185], v[112:115]
	v_mfma_f32_16x16x32_bf16 v[100:103], v[166:169], v[190:193], v[100:103]
	v_mfma_f32_16x16x32_bf16 v[96:99], v[174:177], v[190:193], v[96:99]
	v_mfma_f32_16x16x32_bf16 v[84:87], v[166:169], v[198:201], v[84:87]
	v_mfma_f32_16x16x32_bf16 v[80:83], v[174:177], v[198:201], v[80:83]
	v_mfma_f32_16x16x32_bf16 v[68:71], v[166:169], v[206:209], v[68:71]
	v_mfma_f32_16x16x32_bf16 v[64:67], v[174:177], v[206:209], v[64:67]
	v_mfma_f32_16x16x32_bf16 v[116:119], v[170:173], v[186:189], v[116:119]
	v_mfma_f32_16x16x32_bf16 v[112:115], v[178:181], v[186:189], v[112:115]
	v_mfma_f32_16x16x32_bf16 v[100:103], v[170:173], v[194:197], v[100:103]
	v_mfma_f32_16x16x32_bf16 v[96:99], v[178:181], v[194:197], v[96:99]
	v_mfma_f32_16x16x32_bf16 v[84:87], v[170:173], v[202:205], v[84:87]
	v_mfma_f32_16x16x32_bf16 v[80:83], v[178:181], v[202:205], v[80:83]
	v_mfma_f32_16x16x32_bf16 v[68:71], v[170:173], v[210:213], v[68:71]
	v_mfma_f32_16x16x32_bf16 v[64:67], v[178:181], v[210:213], v[64:67]
	s_setprio 0
	s_barrier
	s_add_i32 s36, s57, s44
	v_lshl_add_u64 v[214:215], v[214:215], 0, s[14:15]
	s_mov_b32 m0, s36
	ds_read_b128 v[182:185], v153 offset:49152
	ds_read_b128 v[186:189], v153 offset:50176
	ds_read_b128 v[190:193], v153 offset:51200
	ds_read_b128 v[194:197], v153 offset:52224
	ds_read_b128 v[198:201], v153 offset:53248
	ds_read_b128 v[202:205], v153 offset:54272
	ds_read_b128 v[206:209], v153 offset:55296
	ds_read_b128 v[210:213], v153 offset:56320
	global_load_lds_dwordx4 v[214:215], off
	s_add_i32 m0, s36, 0x2000
	s_add_u32 s34, s34, 0x100080
	v_lshl_add_u64 v[214:215], v[216:217], 0, s[14:15]
	s_addc_u32 s35, s35, 0
	s_add_i32 s36, s58, s44
	global_load_lds_dwordx4 v[214:215], off
	v_lshl_add_u64 v[214:215], s[34:35], 0, v[130:131]
	s_mov_b32 m0, s36
	s_nop 0
	global_load_lds_dwordx4 v[214:215], off
	v_lshl_add_u64 v[214:215], s[34:35], 0, v[134:135]
	s_add_i32 m0, s36, 0x2000
	s_nop 0
	global_load_lds_dwordx4 v[214:215], off
	v_lshl_add_u64 v[214:215], v[218:219], 0, s[14:15]
	s_mov_b32 m0, s49
	s_nop 0
	global_load_lds_dwordx4 v[214:215], off
	v_lshl_add_u64 v[214:215], v[220:221], 0, s[14:15]
	s_mov_b32 m0, s50
	s_nop 0
	global_load_lds_dwordx4 v[214:215], off
	s_waitcnt vmcnt(8)
	s_waitcnt lgkmcnt(0)
	s_barrier
	s_setprio 1
	v_mfma_f32_16x16x32_bf16 v[60:63], v[144:147], v[182:185], v[60:63]
	v_mfma_f32_16x16x32_bf16 v[56:59], v[158:161], v[182:185], v[56:59]
	v_mfma_f32_16x16x32_bf16 v[44:47], v[144:147], v[190:193], v[44:47]
	v_mfma_f32_16x16x32_bf16 v[40:43], v[158:161], v[190:193], v[40:43]
	v_mfma_f32_16x16x32_bf16 v[28:31], v[144:147], v[198:201], v[28:31]
	v_mfma_f32_16x16x32_bf16 v[24:27], v[158:161], v[198:201], v[24:27]
	v_mfma_f32_16x16x32_bf16 v[12:15], v[144:147], v[206:209], v[12:15]
	v_mfma_f32_16x16x32_bf16 v[8:11], v[158:161], v[206:209], v[8:11]
	v_mfma_f32_16x16x32_bf16 v[60:63], v[154:157], v[186:189], v[60:63]
	v_mfma_f32_16x16x32_bf16 v[56:59], v[162:165], v[186:189], v[56:59]
	v_mfma_f32_16x16x32_bf16 v[44:47], v[154:157], v[194:197], v[44:47]
	v_mfma_f32_16x16x32_bf16 v[40:43], v[162:165], v[194:197], v[40:43]
	v_mfma_f32_16x16x32_bf16 v[28:31], v[154:157], v[202:205], v[28:31]
	v_mfma_f32_16x16x32_bf16 v[24:27], v[162:165], v[202:205], v[24:27]
	v_mfma_f32_16x16x32_bf16 v[12:15], v[154:157], v[210:213], v[12:15]
	v_mfma_f32_16x16x32_bf16 v[8:11], v[162:165], v[210:213], v[8:11]
	s_setprio 0
	s_setprio 1
	v_mfma_f32_16x16x32_bf16 v[52:55], v[166:169], v[182:185], v[52:55]
	v_mfma_f32_16x16x32_bf16 v[48:51], v[174:177], v[182:185], v[48:51]
	v_mfma_f32_16x16x32_bf16 v[36:39], v[166:169], v[190:193], v[36:39]
	v_mfma_f32_16x16x32_bf16 v[32:35], v[174:177], v[190:193], v[32:35]
	v_mfma_f32_16x16x32_bf16 v[20:23], v[166:169], v[198:201], v[20:23]
	v_mfma_f32_16x16x32_bf16 v[16:19], v[174:177], v[198:201], v[16:19]
	v_mfma_f32_16x16x32_bf16 v[4:7], v[166:169], v[206:209], v[4:7]
	v_mfma_f32_16x16x32_bf16 v[0:3], v[174:177], v[206:209], v[0:3]
	v_mfma_f32_16x16x32_bf16 v[52:55], v[170:173], v[186:189], v[52:55]
	v_mfma_f32_16x16x32_bf16 v[48:51], v[178:181], v[186:189], v[48:51]
	v_mfma_f32_16x16x32_bf16 v[36:39], v[170:173], v[194:197], v[36:39]
	v_mfma_f32_16x16x32_bf16 v[32:35], v[178:181], v[194:197], v[32:35]
	v_mfma_f32_16x16x32_bf16 v[20:23], v[170:173], v[202:205], v[20:23]
	v_mfma_f32_16x16x32_bf16 v[16:19], v[178:181], v[202:205], v[16:19]
	v_mfma_f32_16x16x32_bf16 v[4:7], v[170:173], v[210:213], v[4:7]
	v_mfma_f32_16x16x32_bf16 v[0:3], v[178:181], v[210:213], v[0:3]
	s_setprio 0
	s_add_i32 s56, s56, 2
	s_add_u32 s27, s27, 0x100
	s_addc_u32 s55, s55, 0
	s_add_u32 s30, s30, 0x100
	s_addc_u32 s31, s31, 0
	s_cmp_gt_u32 s56, 61
	s_barrier
	s_cbranch_scc0 .LBB0_1363
	s_and_b64 vcc, exec, s[16:17]
	s_cbranch_vccz .LBB0_1366
	s_barrier

.LBB0_1461:
	ds_read_b128 v[144:147], v155
	ds_read_b128 v[148:151], v155 offset:1024
	ds_read_b128 v[160:163], v155 offset:2048
	ds_read_b128 v[164:167], v155 offset:3072
	ds_read_b128 v[168:171], v156
	ds_read_b128 v[172:175], v156 offset:1024
	ds_read_b128 v[176:179], v156 offset:2048
	ds_read_b128 v[180:183], v156 offset:3072
	s_add_u32 s38, s36, 0xfff00080
	s_addc_u32 s39, s37, -1
	s_cmp_eq_u32 s67, 60
	s_cselect_b32 s41, s1, s39
	s_cselect_b32 s40, s5, s38
	s_cselect_b32 s39, s27, s66
	s_cselect_b32 s38, s29, s65
	v_lshl_add_u64 v[216:217], s[36:37], 0, v[138:139]
	s_add_i32 m0, s50, 0xc000
	ds_read_b128 v[184:187], v157
	ds_read_b128 v[188:191], v157 offset:1024
	ds_read_b128 v[192:195], v157 offset:2048
	ds_read_b128 v[196:199], v157 offset:3072
	ds_read_b128 v[200:203], v157 offset:4096
	ds_read_b128 v[204:207], v157 offset:5120
	ds_read_b128 v[208:211], v157 offset:6144
	ds_read_b128 v[212:215], v157 offset:7168
	global_load_lds_dwordx4 v[216:217], off
	v_lshl_add_u64 v[216:217], s[36:37], 0, v[136:137]
	s_add_i32 m0, s50, 0xe000
	s_nop 0
	global_load_lds_dwordx4 v[216:217], off
	s_waitcnt vmcnt(8)
	s_waitcnt lgkmcnt(0)
	s_barrier
	s_setprio 1
	v_mfma_f32_16x16x32_bf16 v[124:127], v[144:147], v[184:187], v[124:127]
	v_mfma_f32_16x16x32_bf16 v[120:123], v[160:163], v[184:187], v[120:123]
	v_mfma_f32_16x16x32_bf16 v[108:111], v[144:147], v[192:195], v[108:111]
	v_mfma_f32_16x16x32_bf16 v[104:107], v[160:163], v[192:195], v[104:107]
	v_mfma_f32_16x16x32_bf16 v[92:95], v[144:147], v[200:203], v[92:95]
	v_mfma_f32_16x16x32_bf16 v[88:91], v[160:163], v[200:203], v[88:91]
	v_mfma_f32_16x16x32_bf16 v[76:79], v[144:147], v[208:211], v[76:79]
	v_mfma_f32_16x16x32_bf16 v[72:75], v[160:163], v[208:211], v[72:75]
	v_mfma_f32_16x16x32_bf16 v[124:127], v[148:151], v[188:191], v[124:127]
	v_mfma_f32_16x16x32_bf16 v[120:123], v[164:167], v[188:191], v[120:123]
	v_mfma_f32_16x16x32_bf16 v[108:111], v[148:151], v[196:199], v[108:111]
	v_mfma_f32_16x16x32_bf16 v[104:107], v[164:167], v[196:199], v[104:107]
	v_mfma_f32_16x16x32_bf16 v[92:95], v[148:151], v[204:207], v[92:95]
	v_mfma_f32_16x16x32_bf16 v[88:91], v[164:167], v[204:207], v[88:91]
	v_mfma_f32_16x16x32_bf16 v[76:79], v[148:151], v[212:215], v[76:79]
	v_mfma_f32_16x16x32_bf16 v[72:75], v[164:167], v[212:215], v[72:75]
	s_setprio 0
	s_setprio 1
	v_mfma_f32_16x16x32_bf16 v[116:119], v[168:171], v[184:187], v[116:119]
	v_mfma_f32_16x16x32_bf16 v[112:115], v[176:179], v[184:187], v[112:115]
	v_mfma_f32_16x16x32_bf16 v[100:103], v[168:171], v[192:195], v[100:103]
	v_mfma_f32_16x16x32_bf16 v[96:99], v[176:179], v[192:195], v[96:99]
	v_mfma_f32_16x16x32_bf16 v[84:87], v[168:171], v[200:203], v[84:87]
	v_mfma_f32_16x16x32_bf16 v[80:83], v[176:179], v[200:203], v[80:83]
	v_mfma_f32_16x16x32_bf16 v[68:71], v[168:171], v[208:211], v[68:71]
	v_mfma_f32_16x16x32_bf16 v[64:67], v[176:179], v[208:211], v[64:67]
	v_mfma_f32_16x16x32_bf16 v[116:119], v[172:175], v[188:191], v[116:119]
	v_mfma_f32_16x16x32_bf16 v[112:115], v[180:183], v[188:191], v[112:115]
	v_mfma_f32_16x16x32_bf16 v[100:103], v[172:175], v[196:199], v[100:103]
	v_mfma_f32_16x16x32_bf16 v[96:99], v[180:183], v[196:199], v[96:99]
	v_mfma_f32_16x16x32_bf16 v[84:87], v[172:175], v[204:207], v[84:87]
	v_mfma_f32_16x16x32_bf16 v[80:83], v[180:183], v[204:207], v[80:83]
	v_mfma_f32_16x16x32_bf16 v[68:71], v[172:175], v[212:215], v[68:71]
	v_mfma_f32_16x16x32_bf16 v[64:67], v[180:183], v[212:215], v[64:67]
	s_setprio 0
	s_barrier
	s_add_i32 s68, s58, s49
	v_lshl_add_u64 v[216:217], s[38:39], 0, v[130:131]
	s_mov_b32 m0, s68
	ds_read_b128 v[184:187], v157 offset:16384
	ds_read_b128 v[188:191], v157 offset:17408
	ds_read_b128 v[192:195], v157 offset:18432
	ds_read_b128 v[196:199], v157 offset:19456
	ds_read_b128 v[200:203], v157 offset:20480
	ds_read_b128 v[204:207], v157 offset:21504
	ds_read_b128 v[208:211], v157 offset:22528
	ds_read_b128 v[212:215], v157 offset:23552
	global_load_lds_dwordx4 v[216:217], off
	s_add_i32 m0, s68, 0x2000
	s_add_u32 s68, s38, 0x100000
	v_lshl_add_u64 v[218:219], s[38:39], 0, v[134:135]
	s_addc_u32 s69, s39, 0
	s_add_i32 s70, s59, s49
	global_load_lds_dwordx4 v[218:219], off
	v_lshl_add_u64 v[220:221], s[68:69], 0, v[130:131]
	s_mov_b32 m0, s70
	v_lshl_add_u64 v[222:223], s[40:41], 0, v[132:133]
	global_load_lds_dwordx4 v[220:221], off
	v_lshl_add_u64 v[220:221], s[68:69], 0, v[134:135]
	s_add_i32 m0, s70, 0x2000
	s_nop 0
	global_load_lds_dwordx4 v[220:221], off
	v_lshl_add_u64 v[220:221], s[40:41], 0, v[128:129]
	s_mov_b32 m0, s50
	s_nop 0
	global_load_lds_dwordx4 v[220:221], off
	s_mov_b32 m0, s51
	s_nop 0
	global_load_lds_dwordx4 v[222:223], off
	s_waitcnt vmcnt(8)
	s_waitcnt lgkmcnt(0)
	s_barrier
	s_setprio 1
	v_mfma_f32_16x16x32_bf16 v[60:63], v[144:147], v[184:187], v[60:63]
	v_mfma_f32_16x16x32_bf16 v[56:59], v[160:163], v[184:187], v[56:59]
	v_mfma_f32_16x16x32_bf16 v[44:47], v[144:147], v[192:195], v[44:47]
	v_mfma_f32_16x16x32_bf16 v[40:43], v[160:163], v[192:195], v[40:43]
	v_mfma_f32_16x16x32_bf16 v[28:31], v[144:147], v[200:203], v[28:31]
	v_mfma_f32_16x16x32_bf16 v[24:27], v[160:163], v[200:203], v[24:27]
	v_mfma_f32_16x16x32_bf16 v[12:15], v[144:147], v[208:211], v[12:15]
	v_mfma_f32_16x16x32_bf16 v[8:11], v[160:163], v[208:211], v[8:11]
	v_mfma_f32_16x16x32_bf16 v[60:63], v[148:151], v[188:191], v[60:63]
	v_mfma_f32_16x16x32_bf16 v[56:59], v[164:167], v[188:191], v[56:59]
	v_mfma_f32_16x16x32_bf16 v[44:47], v[148:151], v[196:199], v[44:47]
	v_mfma_f32_16x16x32_bf16 v[40:43], v[164:167], v[196:199], v[40:43]
	v_mfma_f32_16x16x32_bf16 v[28:31], v[148:151], v[204:207], v[28:31]
	v_mfma_f32_16x16x32_bf16 v[24:27], v[164:167], v[204:207], v[24:27]
	v_mfma_f32_16x16x32_bf16 v[12:15], v[148:151], v[212:215], v[12:15]
	v_mfma_f32_16x16x32_bf16 v[8:11], v[164:167], v[212:215], v[8:11]
	s_setprio 0
	s_setprio 1
	v_mfma_f32_16x16x32_bf16 v[52:55], v[168:171], v[184:187], v[52:55]
	v_mfma_f32_16x16x32_bf16 v[48:51], v[176:179], v[184:187], v[48:51]
	v_mfma_f32_16x16x32_bf16 v[36:39], v[168:171], v[192:195], v[36:39]
	v_mfma_f32_16x16x32_bf16 v[32:35], v[176:179], v[192:195], v[32:35]
	v_mfma_f32_16x16x32_bf16 v[20:23], v[168:171], v[200:203], v[20:23]
	v_mfma_f32_16x16x32_bf16 v[16:19], v[176:179], v[200:203], v[16:19]
	v_mfma_f32_16x16x32_bf16 v[4:7], v[168:171], v[208:211], v[4:7]
	v_mfma_f32_16x16x32_bf16 v[0:3], v[176:179], v[208:211], v[0:3]
	v_mfma_f32_16x16x32_bf16 v[52:55], v[172:175], v[188:191], v[52:55]
	v_mfma_f32_16x16x32_bf16 v[48:51], v[180:183], v[188:191], v[48:51]
	v_mfma_f32_16x16x32_bf16 v[36:39], v[172:175], v[196:199], v[36:39]
	v_mfma_f32_16x16x32_bf16 v[32:35], v[180:183], v[196:199], v[32:35]
	v_mfma_f32_16x16x32_bf16 v[20:23], v[172:175], v[204:207], v[20:23]
	v_mfma_f32_16x16x32_bf16 v[16:19], v[180:183], v[204:207], v[16:19]
	v_mfma_f32_16x16x32_bf16 v[4:7], v[172:175], v[212:215], v[4:7]
	v_mfma_f32_16x16x32_bf16 v[0:3], v[180:183], v[212:215], v[0:3]
	s_setprio 0
	s_barrier
	s_add_i32 s68, 0, 0x18000
	s_add_i32 s69, 0, 0x1c000
	v_add_u32_e32 v164, s68, v153
	v_add_u32_e32 v180, s69, v153
	ds_read_b128 v[144:147], v164
	ds_read_b128 v[148:151], v164 offset:1024
	ds_read_b128 v[160:163], v164 offset:2048
	ds_read_b128 v[164:167], v164 offset:3072
	ds_read_b128 v[168:171], v180
	ds_read_b128 v[172:175], v180 offset:1024
	ds_read_b128 v[176:179], v180 offset:2048
	ds_read_b128 v[180:183], v180 offset:3072
	s_add_u32 s40, s40, 0x100000
	s_addc_u32 s41, s41, 0
	s_mov_b32 m0, s52
	v_lshl_add_u64 v[224:225], s[40:41], 0, v[128:129]
	ds_read_b128 v[184:187], v157 offset:32768
	ds_read_b128 v[188:191], v157 offset:33792
	ds_read_b128 v[192:195], v157 offset:34816
	ds_read_b128 v[196:199], v157 offset:35840
	ds_read_b128 v[200:203], v157 offset:36864
	ds_read_b128 v[204:207], v157 offset:37888
	ds_read_b128 v[208:211], v157 offset:38912
	ds_read_b128 v[212:215], v157 offset:39936
	global_load_lds_dwordx4 v[224:225], off
	v_lshl_add_u64 v[224:225], s[40:41], 0, v[132:133]
	s_mov_b32 m0, s53
	s_nop 0
	global_load_lds_dwordx4 v[224:225], off
	s_waitcnt vmcnt(8)
	s_waitcnt lgkmcnt(0)
	s_barrier
	s_setprio 1
	v_mfma_f32_16x16x32_bf16 v[124:127], v[144:147], v[184:187], v[124:127]
	v_mfma_f32_16x16x32_bf16 v[120:123], v[160:163], v[184:187], v[120:123]
	v_mfma_f32_16x16x32_bf16 v[108:111], v[144:147], v[192:195], v[108:111]
	v_mfma_f32_16x16x32_bf16 v[104:107], v[160:163], v[192:195], v[104:107]
	v_mfma_f32_16x16x32_bf16 v[92:95], v[144:147], v[200:203], v[92:95]
	v_mfma_f32_16x16x32_bf16 v[88:91], v[160:163], v[200:203], v[88:91]
	v_mfma_f32_16x16x32_bf16 v[76:79], v[144:147], v[208:211], v[76:79]
	v_mfma_f32_16x16x32_bf16 v[72:75], v[160:163], v[208:211], v[72:75]
	v_mfma_f32_16x16x32_bf16 v[124:127], v[148:151], v[188:191], v[124:127]
	v_mfma_f32_16x16x32_bf16 v[120:123], v[164:167], v[188:191], v[120:123]
	v_mfma_f32_16x16x32_bf16 v[108:111], v[148:151], v[196:199], v[108:111]
	v_mfma_f32_16x16x32_bf16 v[104:107], v[164:167], v[196:199], v[104:107]
	v_mfma_f32_16x16x32_bf16 v[92:95], v[148:151], v[204:207], v[92:95]
	v_mfma_f32_16x16x32_bf16 v[88:91], v[164:167], v[204:207], v[88:91]
	v_mfma_f32_16x16x32_bf16 v[76:79], v[148:151], v[212:215], v[76:79]
	v_mfma_f32_16x16x32_bf16 v[72:75], v[164:167], v[212:215], v[72:75]
	s_setprio 0
	s_setprio 1
	v_mfma_f32_16x16x32_bf16 v[116:119], v[168:171], v[184:187], v[116:119]
	v_mfma_f32_16x16x32_bf16 v[112:115], v[176:179], v[184:187], v[112:115]
	v_mfma_f32_16x16x32_bf16 v[100:103], v[168:171], v[192:195], v[100:103]
	v_mfma_f32_16x16x32_bf16 v[96:99], v[176:179], v[192:195], v[96:99]
	v_mfma_f32_16x16x32_bf16 v[84:87], v[168:171], v[200:203], v[84:87]
	v_mfma_f32_16x16x32_bf16 v[80:83], v[176:179], v[200:203], v[80:83]
	v_mfma_f32_16x16x32_bf16 v[68:71], v[168:171], v[208:211], v[68:71]
	v_mfma_f32_16x16x32_bf16 v[64:67], v[176:179], v[208:211], v[64:67]
	v_mfma_f32_16x16x32_bf16 v[116:119], v[172:175], v[188:191], v[116:119]
	v_mfma_f32_16x16x32_bf16 v[112:115], v[180:183], v[188:191], v[112:115]
	v_mfma_f32_16x16x32_bf16 v[100:103], v[172:175], v[196:199], v[100:103]
	v_mfma_f32_16x16x32_bf16 v[96:99], v[180:183], v[196:199], v[96:99]
	v_mfma_f32_16x16x32_bf16 v[84:87], v[172:175], v[204:207], v[84:87]
	v_mfma_f32_16x16x32_bf16 v[80:83], v[180:183], v[204:207], v[80:83]
	v_mfma_f32_16x16x32_bf16 v[68:71], v[172:175], v[212:215], v[68:71]
	v_mfma_f32_16x16x32_bf16 v[64:67], v[180:183], v[212:215], v[64:67]
	s_setprio 0
	s_barrier
	s_add_i32 s40, s68, s49
	v_lshl_add_u64 v[216:217], v[216:217], 0, s[14:15]
	s_mov_b32 m0, s40
	ds_read_b128 v[184:187], v157 offset:49152
	ds_read_b128 v[188:191], v157 offset:50176
	ds_read_b128 v[192:195], v157 offset:51200
	ds_read_b128 v[196:199], v157 offset:52224
	ds_read_b128 v[200:203], v157 offset:53248
	ds_read_b128 v[204:207], v157 offset:54272
	ds_read_b128 v[208:211], v157 offset:55296
	ds_read_b128 v[212:215], v157 offset:56320
	global_load_lds_dwordx4 v[216:217], off
	s_add_i32 m0, s40, 0x2000
	s_add_u32 s38, s38, 0x100080
	v_lshl_add_u64 v[216:217], v[218:219], 0, s[14:15]
	s_addc_u32 s39, s39, 0
	s_add_i32 s40, s69, s49
	global_load_lds_dwordx4 v[216:217], off
	v_lshl_add_u64 v[216:217], s[38:39], 0, v[130:131]
	s_mov_b32 m0, s40
	s_nop 0
	global_load_lds_dwordx4 v[216:217], off
	v_lshl_add_u64 v[216:217], s[38:39], 0, v[134:135]
	s_add_i32 m0, s40, 0x2000
	s_nop 0
	global_load_lds_dwordx4 v[216:217], off
	v_lshl_add_u64 v[216:217], v[220:221], 0, s[14:15]
	s_mov_b32 m0, s55
	s_nop 0
	global_load_lds_dwordx4 v[216:217], off
	v_lshl_add_u64 v[216:217], v[222:223], 0, s[14:15]
	s_mov_b32 m0, s56
	s_nop 0
	global_load_lds_dwordx4 v[216:217], off
	s_waitcnt vmcnt(8)
	s_waitcnt lgkmcnt(0)
	s_barrier
	s_setprio 1
	v_mfma_f32_16x16x32_bf16 v[60:63], v[144:147], v[184:187], v[60:63]
	v_mfma_f32_16x16x32_bf16 v[56:59], v[160:163], v[184:187], v[56:59]
	v_mfma_f32_16x16x32_bf16 v[44:47], v[144:147], v[192:195], v[44:47]
	v_mfma_f32_16x16x32_bf16 v[40:43], v[160:163], v[192:195], v[40:43]
	v_mfma_f32_16x16x32_bf16 v[28:31], v[144:147], v[200:203], v[28:31]
	v_mfma_f32_16x16x32_bf16 v[24:27], v[160:163], v[200:203], v[24:27]
	v_mfma_f32_16x16x32_bf16 v[12:15], v[144:147], v[208:211], v[12:15]
	v_mfma_f32_16x16x32_bf16 v[8:11], v[160:163], v[208:211], v[8:11]
	v_mfma_f32_16x16x32_bf16 v[60:63], v[148:151], v[188:191], v[60:63]
	v_mfma_f32_16x16x32_bf16 v[56:59], v[164:167], v[188:191], v[56:59]
	v_mfma_f32_16x16x32_bf16 v[44:47], v[148:151], v[196:199], v[44:47]
	v_mfma_f32_16x16x32_bf16 v[40:43], v[164:167], v[196:199], v[40:43]
	v_mfma_f32_16x16x32_bf16 v[28:31], v[148:151], v[204:207], v[28:31]
	v_mfma_f32_16x16x32_bf16 v[24:27], v[164:167], v[204:207], v[24:27]
	v_mfma_f32_16x16x32_bf16 v[12:15], v[148:151], v[212:215], v[12:15]
	v_mfma_f32_16x16x32_bf16 v[8:11], v[164:167], v[212:215], v[8:11]
	s_setprio 0
	s_setprio 1
	v_mfma_f32_16x16x32_bf16 v[52:55], v[168:171], v[184:187], v[52:55]
	v_mfma_f32_16x16x32_bf16 v[48:51], v[176:179], v[184:187], v[48:51]
	v_mfma_f32_16x16x32_bf16 v[36:39], v[168:171], v[192:195], v[36:39]
	v_mfma_f32_16x16x32_bf16 v[32:35], v[176:179], v[192:195], v[32:35]
	v_mfma_f32_16x16x32_bf16 v[20:23], v[168:171], v[200:203], v[20:23]
	v_mfma_f32_16x16x32_bf16 v[16:19], v[176:179], v[200:203], v[16:19]
	v_mfma_f32_16x16x32_bf16 v[4:7], v[168:171], v[208:211], v[4:7]
	v_mfma_f32_16x16x32_bf16 v[0:3], v[176:179], v[208:211], v[0:3]
	v_mfma_f32_16x16x32_bf16 v[52:55], v[172:175], v[188:191], v[52:55]
	v_mfma_f32_16x16x32_bf16 v[48:51], v[180:183], v[188:191], v[48:51]
	v_mfma_f32_16x16x32_bf16 v[36:39], v[172:175], v[196:199], v[36:39]
	v_mfma_f32_16x16x32_bf16 v[32:35], v[180:183], v[196:199], v[32:35]
	v_mfma_f32_16x16x32_bf16 v[20:23], v[172:175], v[204:207], v[20:23]
	v_mfma_f32_16x16x32_bf16 v[16:19], v[180:183], v[204:207], v[16:19]
	v_mfma_f32_16x16x32_bf16 v[4:7], v[172:175], v[212:215], v[4:7]
	v_mfma_f32_16x16x32_bf16 v[0:3], v[180:183], v[212:215], v[0:3]
	s_setprio 0
	s_add_i32 s67, s67, 2
	s_add_u32 s65, s65, 0x100
	s_addc_u32 s66, s66, 0
	s_add_u32 s36, s36, 0x100
	s_addc_u32 s37, s37, 0
	s_cmp_gt_u32 s67, 61
	s_barrier
	s_cbranch_scc0 .LBB0_1461
	s_and_b64 vcc, exec, s[16:17]
	s_cbranch_vccz .LBB0_1464
	s_barrier

.LBB0_1539:
	ds_read_b128 v[144:147], v151
	ds_read_b128 v[154:157], v151 offset:1024
	ds_read_b128 v[158:161], v151 offset:2048
	ds_read_b128 v[162:165], v151 offset:3072
	ds_read_b128 v[166:169], v152
	ds_read_b128 v[170:173], v152 offset:1024
	ds_read_b128 v[174:177], v152 offset:2048
	ds_read_b128 v[178:181], v152 offset:3072
	s_add_u32 s34, s30, 0xffc00080
	s_addc_u32 s35, s31, -1
	s_cmpk_eq_i32 s56, 0xfc
	s_cselect_b32 s37, s0, s35
	s_cselect_b32 s36, s1, s34
	s_cselect_b32 s35, s19, s55
	s_cselect_b32 s34, s21, s27
	v_lshl_add_u64 v[214:215], s[30:31], 0, v[138:139]
	s_add_i32 m0, s29, 0xc000
	ds_read_b128 v[182:185], v153
	ds_read_b128 v[186:189], v153 offset:1024
	ds_read_b128 v[190:193], v153 offset:2048
	ds_read_b128 v[194:197], v153 offset:3072
	ds_read_b128 v[198:201], v153 offset:4096
	ds_read_b128 v[202:205], v153 offset:5120
	ds_read_b128 v[206:209], v153 offset:6144
	ds_read_b128 v[210:213], v153 offset:7168
	global_load_lds_dwordx4 v[214:215], off
	v_lshl_add_u64 v[214:215], s[30:31], 0, v[136:137]
	s_add_i32 m0, s29, 0xe000
	s_nop 0
	global_load_lds_dwordx4 v[214:215], off
	s_waitcnt vmcnt(8)
	s_waitcnt lgkmcnt(0)
	s_barrier
	s_setprio 1
	v_mfma_f32_16x16x32_bf16 v[124:127], v[144:147], v[182:185], v[124:127]
	v_mfma_f32_16x16x32_bf16 v[120:123], v[158:161], v[182:185], v[120:123]
	v_mfma_f32_16x16x32_bf16 v[108:111], v[144:147], v[190:193], v[108:111]
	v_mfma_f32_16x16x32_bf16 v[104:107], v[158:161], v[190:193], v[104:107]
	v_mfma_f32_16x16x32_bf16 v[92:95], v[144:147], v[198:201], v[92:95]
	v_mfma_f32_16x16x32_bf16 v[88:91], v[158:161], v[198:201], v[88:91]
	v_mfma_f32_16x16x32_bf16 v[76:79], v[144:147], v[206:209], v[76:79]
	v_mfma_f32_16x16x32_bf16 v[72:75], v[158:161], v[206:209], v[72:75]
	v_mfma_f32_16x16x32_bf16 v[124:127], v[154:157], v[186:189], v[124:127]
	v_mfma_f32_16x16x32_bf16 v[120:123], v[162:165], v[186:189], v[120:123]
	v_mfma_f32_16x16x32_bf16 v[108:111], v[154:157], v[194:197], v[108:111]
	v_mfma_f32_16x16x32_bf16 v[104:107], v[162:165], v[194:197], v[104:107]
	v_mfma_f32_16x16x32_bf16 v[92:95], v[154:157], v[202:205], v[92:95]
	v_mfma_f32_16x16x32_bf16 v[88:91], v[162:165], v[202:205], v[88:91]
	v_mfma_f32_16x16x32_bf16 v[76:79], v[154:157], v[210:213], v[76:79]
	v_mfma_f32_16x16x32_bf16 v[72:75], v[162:165], v[210:213], v[72:75]
	s_setprio 0
	s_setprio 1
	v_mfma_f32_16x16x32_bf16 v[116:119], v[166:169], v[182:185], v[116:119]
	v_mfma_f32_16x16x32_bf16 v[112:115], v[174:177], v[182:185], v[112:115]
	v_mfma_f32_16x16x32_bf16 v[100:103], v[166:169], v[190:193], v[100:103]
	v_mfma_f32_16x16x32_bf16 v[96:99], v[174:177], v[190:193], v[96:99]
	v_mfma_f32_16x16x32_bf16 v[84:87], v[166:169], v[198:201], v[84:87]
	v_mfma_f32_16x16x32_bf16 v[80:83], v[174:177], v[198:201], v[80:83]
	v_mfma_f32_16x16x32_bf16 v[68:71], v[166:169], v[206:209], v[68:71]
	v_mfma_f32_16x16x32_bf16 v[64:67], v[174:177], v[206:209], v[64:67]
	v_mfma_f32_16x16x32_bf16 v[116:119], v[170:173], v[186:189], v[116:119]
	v_mfma_f32_16x16x32_bf16 v[112:115], v[178:181], v[186:189], v[112:115]
	v_mfma_f32_16x16x32_bf16 v[100:103], v[170:173], v[194:197], v[100:103]
	v_mfma_f32_16x16x32_bf16 v[96:99], v[178:181], v[194:197], v[96:99]
	v_mfma_f32_16x16x32_bf16 v[84:87], v[170:173], v[202:205], v[84:87]
	v_mfma_f32_16x16x32_bf16 v[80:83], v[178:181], v[202:205], v[80:83]
	v_mfma_f32_16x16x32_bf16 v[68:71], v[170:173], v[210:213], v[68:71]
	v_mfma_f32_16x16x32_bf16 v[64:67], v[178:181], v[210:213], v[64:67]
	s_setprio 0
	s_barrier
	s_add_i32 s57, s53, s44
	v_lshl_add_u64 v[214:215], s[34:35], 0, v[130:131]
	s_mov_b32 m0, s57
	ds_read_b128 v[182:185], v153 offset:16384
	ds_read_b128 v[186:189], v153 offset:17408
	ds_read_b128 v[190:193], v153 offset:18432
	ds_read_b128 v[194:197], v153 offset:19456
	ds_read_b128 v[198:201], v153 offset:20480
	ds_read_b128 v[202:205], v153 offset:21504
	ds_read_b128 v[206:209], v153 offset:22528
	ds_read_b128 v[210:213], v153 offset:23552
	global_load_lds_dwordx4 v[214:215], off
	s_add_i32 m0, s57, 0x2000
	s_add_u32 s58, s34, 0x400000
	v_lshl_add_u64 v[216:217], s[34:35], 0, v[134:135]
	s_addc_u32 s59, s35, 0
	s_add_i32 s57, s54, s44
	global_load_lds_dwordx4 v[216:217], off
	v_lshl_add_u64 v[218:219], s[58:59], 0, v[130:131]
	s_mov_b32 m0, s57
	v_lshl_add_u64 v[220:221], s[36:37], 0, v[132:133]
	global_load_lds_dwordx4 v[218:219], off
	v_lshl_add_u64 v[218:219], s[58:59], 0, v[134:135]
	s_add_i32 m0, s57, 0x2000
	s_nop 0
	global_load_lds_dwordx4 v[218:219], off
	v_lshl_add_u64 v[218:219], s[36:37], 0, v[128:129]
	s_mov_b32 m0, s29
	s_nop 0
	global_load_lds_dwordx4 v[218:219], off
	s_mov_b32 m0, s45
	s_nop 0
	global_load_lds_dwordx4 v[220:221], off
	s_waitcnt vmcnt(8)
	s_waitcnt lgkmcnt(0)
	s_barrier
	s_setprio 1
	v_mfma_f32_16x16x32_bf16 v[60:63], v[144:147], v[182:185], v[60:63]
	v_mfma_f32_16x16x32_bf16 v[56:59], v[158:161], v[182:185], v[56:59]
	v_mfma_f32_16x16x32_bf16 v[44:47], v[144:147], v[190:193], v[44:47]
	v_mfma_f32_16x16x32_bf16 v[40:43], v[158:161], v[190:193], v[40:43]
	v_mfma_f32_16x16x32_bf16 v[28:31], v[144:147], v[198:201], v[28:31]
	v_mfma_f32_16x16x32_bf16 v[24:27], v[158:161], v[198:201], v[24:27]
	v_mfma_f32_16x16x32_bf16 v[12:15], v[144:147], v[206:209], v[12:15]
	v_mfma_f32_16x16x32_bf16 v[8:11], v[158:161], v[206:209], v[8:11]
	v_mfma_f32_16x16x32_bf16 v[60:63], v[154:157], v[186:189], v[60:63]
	v_mfma_f32_16x16x32_bf16 v[56:59], v[162:165], v[186:189], v[56:59]
	v_mfma_f32_16x16x32_bf16 v[44:47], v[154:157], v[194:197], v[44:47]
	v_mfma_f32_16x16x32_bf16 v[40:43], v[162:165], v[194:197], v[40:43]
	v_mfma_f32_16x16x32_bf16 v[28:31], v[154:157], v[202:205], v[28:31]
	v_mfma_f32_16x16x32_bf16 v[24:27], v[162:165], v[202:205], v[24:27]
	v_mfma_f32_16x16x32_bf16 v[12:15], v[154:157], v[210:213], v[12:15]
	v_mfma_f32_16x16x32_bf16 v[8:11], v[162:165], v[210:213], v[8:11]
	s_setprio 0
	s_setprio 1
	v_mfma_f32_16x16x32_bf16 v[52:55], v[166:169], v[182:185], v[52:55]
	v_mfma_f32_16x16x32_bf16 v[48:51], v[174:177], v[182:185], v[48:51]
	v_mfma_f32_16x16x32_bf16 v[36:39], v[166:169], v[190:193], v[36:39]
	v_mfma_f32_16x16x32_bf16 v[32:35], v[174:177], v[190:193], v[32:35]
	v_mfma_f32_16x16x32_bf16 v[20:23], v[166:169], v[198:201], v[20:23]
	v_mfma_f32_16x16x32_bf16 v[16:19], v[174:177], v[198:201], v[16:19]
	v_mfma_f32_16x16x32_bf16 v[4:7], v[166:169], v[206:209], v[4:7]
	v_mfma_f32_16x16x32_bf16 v[0:3], v[174:177], v[206:209], v[0:3]
	v_mfma_f32_16x16x32_bf16 v[52:55], v[170:173], v[186:189], v[52:55]
	v_mfma_f32_16x16x32_bf16 v[48:51], v[178:181], v[186:189], v[48:51]
	v_mfma_f32_16x16x32_bf16 v[36:39], v[170:173], v[194:197], v[36:39]
	v_mfma_f32_16x16x32_bf16 v[32:35], v[178:181], v[194:197], v[32:35]
	v_mfma_f32_16x16x32_bf16 v[20:23], v[170:173], v[202:205], v[20:23]
	v_mfma_f32_16x16x32_bf16 v[16:19], v[178:181], v[202:205], v[16:19]
	v_mfma_f32_16x16x32_bf16 v[4:7], v[170:173], v[210:213], v[4:7]
	v_mfma_f32_16x16x32_bf16 v[0:3], v[178:181], v[210:213], v[0:3]
	s_setprio 0
	s_barrier
	s_add_i32 s57, 0, 0x18000
	s_add_i32 s58, 0, 0x1c000
	v_add_u32_e32 v162, s57, v149
	v_add_u32_e32 v178, s58, v149
	ds_read_b128 v[144:147], v162
	ds_read_b128 v[154:157], v162 offset:1024
	ds_read_b128 v[158:161], v162 offset:2048
	ds_read_b128 v[162:165], v162 offset:3072
	ds_read_b128 v[166:169], v178
	ds_read_b128 v[170:173], v178 offset:1024
	ds_read_b128 v[174:177], v178 offset:2048
	ds_read_b128 v[178:181], v178 offset:3072
	s_add_u32 s36, s36, 0x400000
	s_addc_u32 s37, s37, 0
	s_mov_b32 m0, s46
	v_lshl_add_u64 v[222:223], s[36:37], 0, v[128:129]
	ds_read_b128 v[182:185], v153 offset:32768
	ds_read_b128 v[186:189], v153 offset:33792
	ds_read_b128 v[190:193], v153 offset:34816
	ds_read_b128 v[194:197], v153 offset:35840
	ds_read_b128 v[198:201], v153 offset:36864
	ds_read_b128 v[202:205], v153 offset:37888
	ds_read_b128 v[206:209], v153 offset:38912
	ds_read_b128 v[210:213], v153 offset:39936
	global_load_lds_dwordx4 v[222:223], off
	v_lshl_add_u64 v[222:223], s[36:37], 0, v[132:133]
	s_mov_b32 m0, s47
	s_nop 0
	global_load_lds_dwordx4 v[222:223], off
	s_waitcnt vmcnt(8)
	s_waitcnt lgkmcnt(0)
	s_barrier
	s_setprio 1
	v_mfma_f32_16x16x32_bf16 v[124:127], v[144:147], v[182:185], v[124:127]
	v_mfma_f32_16x16x32_bf16 v[120:123], v[158:161], v[182:185], v[120:123]
	v_mfma_f32_16x16x32_bf16 v[108:111], v[144:147], v[190:193], v[108:111]
	v_mfma_f32_16x16x32_bf16 v[104:107], v[158:161], v[190:193], v[104:107]
	v_mfma_f32_16x16x32_bf16 v[92:95], v[144:147], v[198:201], v[92:95]
	v_mfma_f32_16x16x32_bf16 v[88:91], v[158:161], v[198:201], v[88:91]
	v_mfma_f32_16x16x32_bf16 v[76:79], v[144:147], v[206:209], v[76:79]
	v_mfma_f32_16x16x32_bf16 v[72:75], v[158:161], v[206:209], v[72:75]
	v_mfma_f32_16x16x32_bf16 v[124:127], v[154:157], v[186:189], v[124:127]
	v_mfma_f32_16x16x32_bf16 v[120:123], v[162:165], v[186:189], v[120:123]
	v_mfma_f32_16x16x32_bf16 v[108:111], v[154:157], v[194:197], v[108:111]
	v_mfma_f32_16x16x32_bf16 v[104:107], v[162:165], v[194:197], v[104:107]
	v_mfma_f32_16x16x32_bf16 v[92:95], v[154:157], v[202:205], v[92:95]
	v_mfma_f32_16x16x32_bf16 v[88:91], v[162:165], v[202:205], v[88:91]
	v_mfma_f32_16x16x32_bf16 v[76:79], v[154:157], v[210:213], v[76:79]
	v_mfma_f32_16x16x32_bf16 v[72:75], v[162:165], v[210:213], v[72:75]
	s_setprio 0
	s_setprio 1
	v_mfma_f32_16x16x32_bf16 v[116:119], v[166:169], v[182:185], v[116:119]
	v_mfma_f32_16x16x32_bf16 v[112:115], v[174:177], v[182:185], v[112:115]
	v_mfma_f32_16x16x32_bf16 v[100:103], v[166:169], v[190:193], v[100:103]
	v_mfma_f32_16x16x32_bf16 v[96:99], v[174:177], v[190:193], v[96:99]
	v_mfma_f32_16x16x32_bf16 v[84:87], v[166:169], v[198:201], v[84:87]
	v_mfma_f32_16x16x32_bf16 v[80:83], v[174:177], v[198:201], v[80:83]
	v_mfma_f32_16x16x32_bf16 v[68:71], v[166:169], v[206:209], v[68:71]
	v_mfma_f32_16x16x32_bf16 v[64:67], v[174:177], v[206:209], v[64:67]
	v_mfma_f32_16x16x32_bf16 v[116:119], v[170:173], v[186:189], v[116:119]
	v_mfma_f32_16x16x32_bf16 v[112:115], v[178:181], v[186:189], v[112:115]
	v_mfma_f32_16x16x32_bf16 v[100:103], v[170:173], v[194:197], v[100:103]
	v_mfma_f32_16x16x32_bf16 v[96:99], v[178:181], v[194:197], v[96:99]
	v_mfma_f32_16x16x32_bf16 v[84:87], v[170:173], v[202:205], v[84:87]
	v_mfma_f32_16x16x32_bf16 v[80:83], v[178:181], v[202:205], v[80:83]
	v_mfma_f32_16x16x32_bf16 v[68:71], v[170:173], v[210:213], v[68:71]
	v_mfma_f32_16x16x32_bf16 v[64:67], v[178:181], v[210:213], v[64:67]
	s_setprio 0
	s_barrier
	s_add_i32 s36, s57, s44
	v_lshl_add_u64 v[214:215], v[214:215], 0, s[14:15]
	s_mov_b32 m0, s36
	ds_read_b128 v[182:185], v153 offset:49152
	ds_read_b128 v[186:189], v153 offset:50176
	ds_read_b128 v[190:193], v153 offset:51200
	ds_read_b128 v[194:197], v153 offset:52224
	ds_read_b128 v[198:201], v153 offset:53248
	ds_read_b128 v[202:205], v153 offset:54272
	ds_read_b128 v[206:209], v153 offset:55296
	ds_read_b128 v[210:213], v153 offset:56320
	global_load_lds_dwordx4 v[214:215], off
	s_add_i32 m0, s36, 0x2000
	s_add_u32 s34, s34, 0x400080
	v_lshl_add_u64 v[214:215], v[216:217], 0, s[14:15]
	s_addc_u32 s35, s35, 0
	s_add_i32 s36, s58, s44
	global_load_lds_dwordx4 v[214:215], off
	v_lshl_add_u64 v[214:215], s[34:35], 0, v[130:131]
	s_mov_b32 m0, s36
	s_nop 0
	global_load_lds_dwordx4 v[214:215], off
	v_lshl_add_u64 v[214:215], s[34:35], 0, v[134:135]
	s_add_i32 m0, s36, 0x2000
	s_nop 0
	global_load_lds_dwordx4 v[214:215], off
	v_lshl_add_u64 v[214:215], v[218:219], 0, s[14:15]
	s_mov_b32 m0, s49
	s_nop 0
	global_load_lds_dwordx4 v[214:215], off
	v_lshl_add_u64 v[214:215], v[220:221], 0, s[14:15]
	s_mov_b32 m0, s50
	s_nop 0
	global_load_lds_dwordx4 v[214:215], off
	s_waitcnt vmcnt(8)
	s_waitcnt lgkmcnt(0)
	s_barrier
	s_setprio 1
	v_mfma_f32_16x16x32_bf16 v[60:63], v[144:147], v[182:185], v[60:63]
	v_mfma_f32_16x16x32_bf16 v[56:59], v[158:161], v[182:185], v[56:59]
	v_mfma_f32_16x16x32_bf16 v[44:47], v[144:147], v[190:193], v[44:47]
	v_mfma_f32_16x16x32_bf16 v[40:43], v[158:161], v[190:193], v[40:43]
	v_mfma_f32_16x16x32_bf16 v[28:31], v[144:147], v[198:201], v[28:31]
	v_mfma_f32_16x16x32_bf16 v[24:27], v[158:161], v[198:201], v[24:27]
	v_mfma_f32_16x16x32_bf16 v[12:15], v[144:147], v[206:209], v[12:15]
	v_mfma_f32_16x16x32_bf16 v[8:11], v[158:161], v[206:209], v[8:11]
	v_mfma_f32_16x16x32_bf16 v[60:63], v[154:157], v[186:189], v[60:63]
	v_mfma_f32_16x16x32_bf16 v[56:59], v[162:165], v[186:189], v[56:59]
	v_mfma_f32_16x16x32_bf16 v[44:47], v[154:157], v[194:197], v[44:47]
	v_mfma_f32_16x16x32_bf16 v[40:43], v[162:165], v[194:197], v[40:43]
	v_mfma_f32_16x16x32_bf16 v[28:31], v[154:157], v[202:205], v[28:31]
	v_mfma_f32_16x16x32_bf16 v[24:27], v[162:165], v[202:205], v[24:27]
	v_mfma_f32_16x16x32_bf16 v[12:15], v[154:157], v[210:213], v[12:15]
	v_mfma_f32_16x16x32_bf16 v[8:11], v[162:165], v[210:213], v[8:11]
	s_setprio 0
	s_setprio 1
	v_mfma_f32_16x16x32_bf16 v[52:55], v[166:169], v[182:185], v[52:55]
	v_mfma_f32_16x16x32_bf16 v[48:51], v[174:177], v[182:185], v[48:51]
	v_mfma_f32_16x16x32_bf16 v[36:39], v[166:169], v[190:193], v[36:39]
	v_mfma_f32_16x16x32_bf16 v[32:35], v[174:177], v[190:193], v[32:35]
	v_mfma_f32_16x16x32_bf16 v[20:23], v[166:169], v[198:201], v[20:23]
	v_mfma_f32_16x16x32_bf16 v[16:19], v[174:177], v[198:201], v[16:19]
	v_mfma_f32_16x16x32_bf16 v[4:7], v[166:169], v[206:209], v[4:7]
	v_mfma_f32_16x16x32_bf16 v[0:3], v[174:177], v[206:209], v[0:3]
	v_mfma_f32_16x16x32_bf16 v[52:55], v[170:173], v[186:189], v[52:55]
	v_mfma_f32_16x16x32_bf16 v[48:51], v[178:181], v[186:189], v[48:51]
	v_mfma_f32_16x16x32_bf16 v[36:39], v[170:173], v[194:197], v[36:39]
	v_mfma_f32_16x16x32_bf16 v[32:35], v[178:181], v[194:197], v[32:35]
	v_mfma_f32_16x16x32_bf16 v[20:23], v[170:173], v[202:205], v[20:23]
	v_mfma_f32_16x16x32_bf16 v[16:19], v[178:181], v[202:205], v[16:19]
	v_mfma_f32_16x16x32_bf16 v[4:7], v[170:173], v[210:213], v[4:7]
	v_mfma_f32_16x16x32_bf16 v[0:3], v[178:181], v[210:213], v[0:3]
	s_setprio 0
	s_add_i32 s56, s56, 2
	s_add_u32 s27, s27, 0x100
	s_addc_u32 s55, s55, 0
	s_add_u32 s30, s30, 0x100
	s_addc_u32 s31, s31, 0
	s_cmpk_gt_u32 s56, 0xfd
	s_barrier
	s_cbranch_scc0 .LBB0_1539
	s_and_b64 vcc, exec, s[16:17]
	s_cbranch_vccz .LBB0_1542
	s_barrier

.LBB0_1945:
	ds_read_b128 v[146:149], v143
	ds_read_b128 v[150:153], v143 offset:1024
	ds_read_b128 v[154:157], v143 offset:2048
	ds_read_b128 v[158:161], v143 offset:3072
	ds_read_b128 v[162:165], v144
	ds_read_b128 v[166:169], v144 offset:1024
	ds_read_b128 v[170:173], v144 offset:2048
	ds_read_b128 v[174:177], v144 offset:3072
	s_add_u32 s38, s36, 0xfff00080
	s_addc_u32 s39, s37, -1
	s_cmp_eq_u32 s61, 4
	s_cselect_b32 s41, s5, s39
	s_cselect_b32 s40, s4, s38
	s_cselect_b32 s39, s29, s60
	s_cselect_b32 s38, s31, s59
	v_lshl_add_u64 v[210:211], s[36:37], 0, v[134:135]
	s_add_i32 m0, s17, 0xc000
	ds_read_b128 v[178:181], v145
	ds_read_b128 v[182:185], v145 offset:1024
	ds_read_b128 v[186:189], v145 offset:2048
	ds_read_b128 v[190:193], v145 offset:3072
	ds_read_b128 v[194:197], v145 offset:4096
	ds_read_b128 v[198:201], v145 offset:5120
	ds_read_b128 v[202:205], v145 offset:6144
	ds_read_b128 v[206:209], v145 offset:7168
	global_load_lds_dwordx4 v[210:211], off
	v_lshl_add_u64 v[210:211], s[36:37], 0, v[132:133]
	s_add_i32 m0, s17, 0xe000
	s_nop 0
	global_load_lds_dwordx4 v[210:211], off
	s_waitcnt vmcnt(8)
	s_waitcnt lgkmcnt(0)
	s_barrier
	s_setprio 1
	v_mfma_f32_16x16x32_bf16 v[124:127], v[146:149], v[178:181], v[124:127]
	v_mfma_f32_16x16x32_bf16 v[120:123], v[154:157], v[178:181], v[120:123]
	v_mfma_f32_16x16x32_bf16 v[116:119], v[146:149], v[186:189], v[116:119]
	v_mfma_f32_16x16x32_bf16 v[112:115], v[154:157], v[186:189], v[112:115]
	v_mfma_f32_16x16x32_bf16 v[100:103], v[146:149], v[194:197], v[100:103]
	v_mfma_f32_16x16x32_bf16 v[96:99], v[154:157], v[194:197], v[96:99]
	v_mfma_f32_16x16x32_bf16 v[84:87], v[146:149], v[202:205], v[84:87]
	v_mfma_f32_16x16x32_bf16 v[80:83], v[154:157], v[202:205], v[80:83]
	v_mfma_f32_16x16x32_bf16 v[124:127], v[150:153], v[182:185], v[124:127]
	v_mfma_f32_16x16x32_bf16 v[120:123], v[158:161], v[182:185], v[120:123]
	v_mfma_f32_16x16x32_bf16 v[116:119], v[150:153], v[190:193], v[116:119]
	v_mfma_f32_16x16x32_bf16 v[112:115], v[158:161], v[190:193], v[112:115]
	v_mfma_f32_16x16x32_bf16 v[100:103], v[150:153], v[198:201], v[100:103]
	v_mfma_f32_16x16x32_bf16 v[96:99], v[158:161], v[198:201], v[96:99]
	v_mfma_f32_16x16x32_bf16 v[84:87], v[150:153], v[206:209], v[84:87]
	v_mfma_f32_16x16x32_bf16 v[80:83], v[158:161], v[206:209], v[80:83]
	s_setprio 0
	s_setprio 1
	v_mfma_f32_16x16x32_bf16 v[108:111], v[162:165], v[178:181], v[108:111]
	v_mfma_f32_16x16x32_bf16 v[104:107], v[170:173], v[178:181], v[104:107]
	v_mfma_f32_16x16x32_bf16 v[92:95], v[162:165], v[186:189], v[92:95]
	v_mfma_f32_16x16x32_bf16 v[88:91], v[170:173], v[186:189], v[88:91]
	v_mfma_f32_16x16x32_bf16 v[76:79], v[162:165], v[194:197], v[76:79]
	v_mfma_f32_16x16x32_bf16 v[72:75], v[170:173], v[194:197], v[72:75]
	v_mfma_f32_16x16x32_bf16 v[68:71], v[162:165], v[202:205], v[68:71]
	v_mfma_f32_16x16x32_bf16 v[64:67], v[170:173], v[202:205], v[64:67]
	v_mfma_f32_16x16x32_bf16 v[108:111], v[166:169], v[182:185], v[108:111]
	v_mfma_f32_16x16x32_bf16 v[104:107], v[174:177], v[182:185], v[104:107]
	v_mfma_f32_16x16x32_bf16 v[92:95], v[166:169], v[190:193], v[92:95]
	v_mfma_f32_16x16x32_bf16 v[88:91], v[174:177], v[190:193], v[88:91]
	v_mfma_f32_16x16x32_bf16 v[76:79], v[166:169], v[198:201], v[76:79]
	v_mfma_f32_16x16x32_bf16 v[72:75], v[174:177], v[198:201], v[72:75]
	v_mfma_f32_16x16x32_bf16 v[68:71], v[166:169], v[206:209], v[68:71]
	v_mfma_f32_16x16x32_bf16 v[64:67], v[174:177], v[206:209], v[64:67]
	s_setprio 0
	s_barrier
	s_add_i32 s62, s54, s46
	v_lshl_add_u64 v[210:211], s[38:39], 0, v[130:131]
	s_mov_b32 m0, s62
	ds_read_b128 v[178:181], v145 offset:16384
	ds_read_b128 v[182:185], v145 offset:17408
	ds_read_b128 v[186:189], v145 offset:18432
	ds_read_b128 v[190:193], v145 offset:19456
	ds_read_b128 v[194:197], v145 offset:20480
	ds_read_b128 v[198:201], v145 offset:21504
	ds_read_b128 v[202:205], v145 offset:22528
	ds_read_b128 v[206:209], v145 offset:23552
	global_load_lds_dwordx4 v[210:211], off
	s_add_i32 m0, s62, 0x2000
	s_add_u32 s62, s38, 0x100000
	v_lshl_add_u64 v[212:213], s[38:39], 0, v[128:129]
	s_addc_u32 s63, s39, 0
	s_add_i32 s64, s55, s46
	global_load_lds_dwordx4 v[212:213], off
	v_lshl_add_u64 v[214:215], s[62:63], 0, v[130:131]
	s_mov_b32 m0, s64
	v_lshl_add_u64 v[216:217], s[40:41], 0, v[128:129]
	global_load_lds_dwordx4 v[214:215], off
	v_lshl_add_u64 v[214:215], s[62:63], 0, v[128:129]
	s_add_i32 m0, s64, 0x2000
	s_nop 0
	global_load_lds_dwordx4 v[214:215], off
	v_lshl_add_u64 v[214:215], s[40:41], 0, v[130:131]
	s_mov_b32 m0, s17
	s_nop 0
	global_load_lds_dwordx4 v[214:215], off
	s_mov_b32 m0, s19
	s_nop 0
	global_load_lds_dwordx4 v[216:217], off
	s_waitcnt vmcnt(8)
	s_waitcnt lgkmcnt(0)
	s_barrier
	s_setprio 1
	v_mfma_f32_16x16x32_bf16 v[60:63], v[146:149], v[178:181], v[60:63]
	v_mfma_f32_16x16x32_bf16 v[56:59], v[154:157], v[178:181], v[56:59]
	v_mfma_f32_16x16x32_bf16 v[52:55], v[146:149], v[186:189], v[52:55]
	v_mfma_f32_16x16x32_bf16 v[48:51], v[154:157], v[186:189], v[48:51]
	v_mfma_f32_16x16x32_bf16 v[40:43], v[146:149], v[194:197], v[40:43]
	v_mfma_f32_16x16x32_bf16 v[32:35], v[154:157], v[194:197], v[32:35]
	v_mfma_f32_16x16x32_bf16 v[24:27], v[146:149], v[202:205], v[24:27]
	v_mfma_f32_16x16x32_bf16 v[16:19], v[154:157], v[202:205], v[16:19]
	v_mfma_f32_16x16x32_bf16 v[60:63], v[150:153], v[182:185], v[60:63]
	v_mfma_f32_16x16x32_bf16 v[56:59], v[158:161], v[182:185], v[56:59]
	v_mfma_f32_16x16x32_bf16 v[52:55], v[150:153], v[190:193], v[52:55]
	v_mfma_f32_16x16x32_bf16 v[48:51], v[158:161], v[190:193], v[48:51]
	v_mfma_f32_16x16x32_bf16 v[40:43], v[150:153], v[198:201], v[40:43]
	v_mfma_f32_16x16x32_bf16 v[32:35], v[158:161], v[198:201], v[32:35]
	v_mfma_f32_16x16x32_bf16 v[24:27], v[150:153], v[206:209], v[24:27]
	v_mfma_f32_16x16x32_bf16 v[16:19], v[158:161], v[206:209], v[16:19]
	s_setprio 0
	s_setprio 1
	v_mfma_f32_16x16x32_bf16 v[44:47], v[162:165], v[178:181], v[44:47]
	v_mfma_f32_16x16x32_bf16 v[36:39], v[170:173], v[178:181], v[36:39]
	v_mfma_f32_16x16x32_bf16 v[28:31], v[162:165], v[186:189], v[28:31]
	v_mfma_f32_16x16x32_bf16 v[20:23], v[170:173], v[186:189], v[20:23]
	v_mfma_f32_16x16x32_bf16 v[12:15], v[162:165], v[194:197], v[12:15]
	v_mfma_f32_16x16x32_bf16 v[8:11], v[170:173], v[194:197], v[8:11]
	v_mfma_f32_16x16x32_bf16 v[4:7], v[162:165], v[202:205], v[4:7]
	v_mfma_f32_16x16x32_bf16 v[0:3], v[170:173], v[202:205], v[0:3]
	v_mfma_f32_16x16x32_bf16 v[44:47], v[166:169], v[182:185], v[44:47]
	v_mfma_f32_16x16x32_bf16 v[36:39], v[174:177], v[182:185], v[36:39]
	v_mfma_f32_16x16x32_bf16 v[28:31], v[166:169], v[190:193], v[28:31]
	v_mfma_f32_16x16x32_bf16 v[20:23], v[174:177], v[190:193], v[20:23]
	v_mfma_f32_16x16x32_bf16 v[12:15], v[166:169], v[198:201], v[12:15]
	v_mfma_f32_16x16x32_bf16 v[8:11], v[174:177], v[198:201], v[8:11]
	v_mfma_f32_16x16x32_bf16 v[4:7], v[166:169], v[206:209], v[4:7]
	v_mfma_f32_16x16x32_bf16 v[0:3], v[174:177], v[206:209], v[0:3]
	s_setprio 0
	s_barrier
	s_add_i32 s62, 0, 0x18000
	s_add_i32 s63, 0, 0x1c000
	v_add_u32_e32 v158, s62, v141
	v_add_u32_e32 v174, s63, v141
	ds_read_b128 v[146:149], v158
	ds_read_b128 v[150:153], v158 offset:1024
	ds_read_b128 v[154:157], v158 offset:2048
	ds_read_b128 v[158:161], v158 offset:3072
	ds_read_b128 v[162:165], v174
	ds_read_b128 v[166:169], v174 offset:1024
	ds_read_b128 v[170:173], v174 offset:2048
	ds_read_b128 v[174:177], v174 offset:3072
	s_add_u32 s40, s40, 0x100000
	s_addc_u32 s41, s41, 0
	s_mov_b32 m0, s48
	v_lshl_add_u64 v[218:219], s[40:41], 0, v[130:131]
	ds_read_b128 v[178:181], v145 offset:32768
	ds_read_b128 v[182:185], v145 offset:33792
	ds_read_b128 v[186:189], v145 offset:34816
	ds_read_b128 v[190:193], v145 offset:35840
	ds_read_b128 v[194:197], v145 offset:36864
	ds_read_b128 v[198:201], v145 offset:37888
	ds_read_b128 v[202:205], v145 offset:38912
	ds_read_b128 v[206:209], v145 offset:39936
	global_load_lds_dwordx4 v[218:219], off
	v_lshl_add_u64 v[218:219], s[40:41], 0, v[128:129]
	s_mov_b32 m0, s49
	s_nop 0
	global_load_lds_dwordx4 v[218:219], off
	s_waitcnt vmcnt(8)
	s_waitcnt lgkmcnt(0)
	s_barrier
	s_setprio 1
	v_mfma_f32_16x16x32_bf16 v[124:127], v[146:149], v[178:181], v[124:127]
	v_mfma_f32_16x16x32_bf16 v[120:123], v[154:157], v[178:181], v[120:123]
	v_mfma_f32_16x16x32_bf16 v[116:119], v[146:149], v[186:189], v[116:119]
	v_mfma_f32_16x16x32_bf16 v[112:115], v[154:157], v[186:189], v[112:115]
	v_mfma_f32_16x16x32_bf16 v[100:103], v[146:149], v[194:197], v[100:103]
	v_mfma_f32_16x16x32_bf16 v[96:99], v[154:157], v[194:197], v[96:99]
	v_mfma_f32_16x16x32_bf16 v[84:87], v[146:149], v[202:205], v[84:87]
	v_mfma_f32_16x16x32_bf16 v[80:83], v[154:157], v[202:205], v[80:83]
	v_mfma_f32_16x16x32_bf16 v[124:127], v[150:153], v[182:185], v[124:127]
	v_mfma_f32_16x16x32_bf16 v[120:123], v[158:161], v[182:185], v[120:123]
	v_mfma_f32_16x16x32_bf16 v[116:119], v[150:153], v[190:193], v[116:119]
	v_mfma_f32_16x16x32_bf16 v[112:115], v[158:161], v[190:193], v[112:115]
	v_mfma_f32_16x16x32_bf16 v[100:103], v[150:153], v[198:201], v[100:103]
	v_mfma_f32_16x16x32_bf16 v[96:99], v[158:161], v[198:201], v[96:99]
	v_mfma_f32_16x16x32_bf16 v[84:87], v[150:153], v[206:209], v[84:87]
	v_mfma_f32_16x16x32_bf16 v[80:83], v[158:161], v[206:209], v[80:83]
	s_setprio 0
	s_setprio 1
	v_mfma_f32_16x16x32_bf16 v[108:111], v[162:165], v[178:181], v[108:111]
	v_mfma_f32_16x16x32_bf16 v[104:107], v[170:173], v[178:181], v[104:107]
	v_mfma_f32_16x16x32_bf16 v[92:95], v[162:165], v[186:189], v[92:95]
	v_mfma_f32_16x16x32_bf16 v[88:91], v[170:173], v[186:189], v[88:91]
	v_mfma_f32_16x16x32_bf16 v[76:79], v[162:165], v[194:197], v[76:79]
	v_mfma_f32_16x16x32_bf16 v[72:75], v[170:173], v[194:197], v[72:75]
	v_mfma_f32_16x16x32_bf16 v[68:71], v[162:165], v[202:205], v[68:71]
	v_mfma_f32_16x16x32_bf16 v[64:67], v[170:173], v[202:205], v[64:67]
	v_mfma_f32_16x16x32_bf16 v[108:111], v[166:169], v[182:185], v[108:111]
	v_mfma_f32_16x16x32_bf16 v[104:107], v[174:177], v[182:185], v[104:107]
	v_mfma_f32_16x16x32_bf16 v[92:95], v[166:169], v[190:193], v[92:95]
	v_mfma_f32_16x16x32_bf16 v[88:91], v[174:177], v[190:193], v[88:91]
	v_mfma_f32_16x16x32_bf16 v[76:79], v[166:169], v[198:201], v[76:79]
	v_mfma_f32_16x16x32_bf16 v[72:75], v[174:177], v[198:201], v[72:75]
	v_mfma_f32_16x16x32_bf16 v[68:71], v[166:169], v[206:209], v[68:71]
	v_mfma_f32_16x16x32_bf16 v[64:67], v[174:177], v[206:209], v[64:67]
	s_setprio 0
	s_barrier
	s_add_i32 s40, s62, s46
	v_lshl_add_u64 v[210:211], v[210:211], 0, s[14:15]
	s_mov_b32 m0, s40
	ds_read_b128 v[178:181], v145 offset:49152
	ds_read_b128 v[182:185], v145 offset:50176
	ds_read_b128 v[186:189], v145 offset:51200
	ds_read_b128 v[190:193], v145 offset:52224
	ds_read_b128 v[194:197], v145 offset:53248
	ds_read_b128 v[198:201], v145 offset:54272
	ds_read_b128 v[202:205], v145 offset:55296
	ds_read_b128 v[206:209], v145 offset:56320
	global_load_lds_dwordx4 v[210:211], off
	s_add_i32 m0, s40, 0x2000
	s_add_u32 s38, s38, 0x100080
	v_lshl_add_u64 v[210:211], v[212:213], 0, s[14:15]
	s_addc_u32 s39, s39, 0
	s_add_i32 s40, s63, s46
	global_load_lds_dwordx4 v[210:211], off
	v_lshl_add_u64 v[210:211], s[38:39], 0, v[130:131]
	s_mov_b32 m0, s40
	s_nop 0
	global_load_lds_dwordx4 v[210:211], off
	v_lshl_add_u64 v[210:211], s[38:39], 0, v[128:129]
	s_add_i32 m0, s40, 0x2000
	s_nop 0
	global_load_lds_dwordx4 v[210:211], off
	v_lshl_add_u64 v[210:211], v[214:215], 0, s[14:15]
	s_mov_b32 m0, s51
	s_nop 0
	global_load_lds_dwordx4 v[210:211], off
	v_lshl_add_u64 v[210:211], v[216:217], 0, s[14:15]
	s_mov_b32 m0, s52
	s_nop 0
	global_load_lds_dwordx4 v[210:211], off
	s_waitcnt vmcnt(8)
	s_waitcnt lgkmcnt(0)
	s_barrier
	s_setprio 1
	v_mfma_f32_16x16x32_bf16 v[60:63], v[146:149], v[178:181], v[60:63]
	v_mfma_f32_16x16x32_bf16 v[56:59], v[154:157], v[178:181], v[56:59]
	v_mfma_f32_16x16x32_bf16 v[52:55], v[146:149], v[186:189], v[52:55]
	v_mfma_f32_16x16x32_bf16 v[48:51], v[154:157], v[186:189], v[48:51]
	v_mfma_f32_16x16x32_bf16 v[40:43], v[146:149], v[194:197], v[40:43]
	v_mfma_f32_16x16x32_bf16 v[32:35], v[154:157], v[194:197], v[32:35]
	v_mfma_f32_16x16x32_bf16 v[24:27], v[146:149], v[202:205], v[24:27]
	v_mfma_f32_16x16x32_bf16 v[16:19], v[154:157], v[202:205], v[16:19]
	v_mfma_f32_16x16x32_bf16 v[60:63], v[150:153], v[182:185], v[60:63]
	v_mfma_f32_16x16x32_bf16 v[56:59], v[158:161], v[182:185], v[56:59]
	v_mfma_f32_16x16x32_bf16 v[52:55], v[150:153], v[190:193], v[52:55]
	v_mfma_f32_16x16x32_bf16 v[48:51], v[158:161], v[190:193], v[48:51]
	v_mfma_f32_16x16x32_bf16 v[40:43], v[150:153], v[198:201], v[40:43]
	v_mfma_f32_16x16x32_bf16 v[32:35], v[158:161], v[198:201], v[32:35]
	v_mfma_f32_16x16x32_bf16 v[24:27], v[150:153], v[206:209], v[24:27]
	v_mfma_f32_16x16x32_bf16 v[16:19], v[158:161], v[206:209], v[16:19]
	s_setprio 0
	s_setprio 1
	v_mfma_f32_16x16x32_bf16 v[44:47], v[162:165], v[178:181], v[44:47]
	v_mfma_f32_16x16x32_bf16 v[36:39], v[170:173], v[178:181], v[36:39]
	v_mfma_f32_16x16x32_bf16 v[28:31], v[162:165], v[186:189], v[28:31]
	v_mfma_f32_16x16x32_bf16 v[20:23], v[170:173], v[186:189], v[20:23]
	v_mfma_f32_16x16x32_bf16 v[12:15], v[162:165], v[194:197], v[12:15]
	v_mfma_f32_16x16x32_bf16 v[8:11], v[170:173], v[194:197], v[8:11]
	v_mfma_f32_16x16x32_bf16 v[4:7], v[162:165], v[202:205], v[4:7]
	v_mfma_f32_16x16x32_bf16 v[0:3], v[170:173], v[202:205], v[0:3]
	v_mfma_f32_16x16x32_bf16 v[44:47], v[166:169], v[182:185], v[44:47]
	v_mfma_f32_16x16x32_bf16 v[36:39], v[174:177], v[182:185], v[36:39]
	v_mfma_f32_16x16x32_bf16 v[28:31], v[166:169], v[190:193], v[28:31]
	v_mfma_f32_16x16x32_bf16 v[20:23], v[174:177], v[190:193], v[20:23]
	v_mfma_f32_16x16x32_bf16 v[12:15], v[166:169], v[198:201], v[12:15]
	v_mfma_f32_16x16x32_bf16 v[8:11], v[174:177], v[198:201], v[8:11]
	v_mfma_f32_16x16x32_bf16 v[4:7], v[166:169], v[206:209], v[4:7]
	v_mfma_f32_16x16x32_bf16 v[0:3], v[174:177], v[206:209], v[0:3]
	s_setprio 0
	s_add_i32 s61, s61, 2
	s_add_u32 s59, s59, 0x100
	s_addc_u32 s60, s60, 0
	s_add_u32 s36, s36, 0x100
	s_addc_u32 s37, s37, 0
	s_cmp_gt_u32 s61, 5
	s_barrier
	s_cbranch_scc0 .LBB0_1945
	s_and_b64 vcc, exec, s[20:21]
	s_cbranch_vccz .LBB0_1948
	s_barrier

.LBB0_3161:
	ds_read_b128 v[152:155], v149
	ds_read_b128 v[156:159], v149 offset:1024
	ds_read_b128 v[160:163], v149 offset:2048
	ds_read_b128 v[164:167], v149 offset:3072
	ds_read_b128 v[168:171], v150
	ds_read_b128 v[172:175], v150 offset:1024
	ds_read_b128 v[176:179], v150 offset:2048
	ds_read_b128 v[180:183], v150 offset:3072
	s_add_u32 s36, s34, 0xffc00080
	s_addc_u32 s37, s35, -1
	s_cmpk_eq_i32 s64, 0xfc
	s_cselect_b32 s39, s25, s37
	s_cselect_b32 s38, s60, s36
	s_cselect_b32 s37, s23, s63
	s_cselect_b32 s36, s61, s62
	v_lshl_add_u64 v[144:145], s[34:35], 0, v[138:139]
	s_add_i32 m0, s31, 0xc000
	ds_read_b128 v[184:187], v151
	ds_read_b128 v[188:191], v151 offset:1024
	ds_read_b128 v[192:195], v151 offset:2048
	ds_read_b128 v[196:199], v151 offset:3072
	ds_read_b128 v[200:203], v151 offset:4096
	ds_read_b128 v[204:207], v151 offset:5120
	ds_read_b128 v[208:211], v151 offset:6144
	ds_read_b128 v[212:215], v151 offset:7168
	global_load_lds_dwordx4 v[144:145], off
	v_lshl_add_u64 v[144:145], s[34:35], 0, v[136:137]
	s_add_i32 m0, s31, 0xe000
	s_nop 0
	global_load_lds_dwordx4 v[144:145], off
	s_waitcnt vmcnt(8)
	s_waitcnt lgkmcnt(0)
	s_barrier
	s_setprio 1
	v_mfma_f32_16x16x32_bf16 v[124:127], v[152:155], v[184:187], v[124:127]
	v_mfma_f32_16x16x32_bf16 v[120:123], v[160:163], v[184:187], v[120:123]
	v_mfma_f32_16x16x32_bf16 v[112:115], v[152:155], v[192:195], v[112:115]
	v_mfma_f32_16x16x32_bf16 v[104:107], v[160:163], v[192:195], v[104:107]
	v_mfma_f32_16x16x32_bf16 v[96:99], v[152:155], v[200:203], v[96:99]
	v_mfma_f32_16x16x32_bf16 v[88:91], v[160:163], v[200:203], v[88:91]
	v_mfma_f32_16x16x32_bf16 v[80:83], v[152:155], v[208:211], v[80:83]
	v_mfma_f32_16x16x32_bf16 v[72:75], v[160:163], v[208:211], v[72:75]
	v_mfma_f32_16x16x32_bf16 v[124:127], v[156:159], v[188:191], v[124:127]
	v_mfma_f32_16x16x32_bf16 v[120:123], v[164:167], v[188:191], v[120:123]
	v_mfma_f32_16x16x32_bf16 v[112:115], v[156:159], v[196:199], v[112:115]
	v_mfma_f32_16x16x32_bf16 v[104:107], v[164:167], v[196:199], v[104:107]
	v_mfma_f32_16x16x32_bf16 v[96:99], v[156:159], v[204:207], v[96:99]
	v_mfma_f32_16x16x32_bf16 v[88:91], v[164:167], v[204:207], v[88:91]
	v_mfma_f32_16x16x32_bf16 v[80:83], v[156:159], v[212:215], v[80:83]
	v_mfma_f32_16x16x32_bf16 v[72:75], v[164:167], v[212:215], v[72:75]
	s_setprio 0
	s_setprio 1
	v_mfma_f32_16x16x32_bf16 v[116:119], v[168:171], v[184:187], v[116:119]
	v_mfma_f32_16x16x32_bf16 v[108:111], v[176:179], v[184:187], v[108:111]
	v_mfma_f32_16x16x32_bf16 v[100:103], v[168:171], v[192:195], v[100:103]
	v_mfma_f32_16x16x32_bf16 v[92:95], v[176:179], v[192:195], v[92:95]
	v_mfma_f32_16x16x32_bf16 v[84:87], v[168:171], v[200:203], v[84:87]
	v_mfma_f32_16x16x32_bf16 v[76:79], v[176:179], v[200:203], v[76:79]
	v_mfma_f32_16x16x32_bf16 v[68:71], v[168:171], v[208:211], v[68:71]
	v_mfma_f32_16x16x32_bf16 v[64:67], v[176:179], v[208:211], v[64:67]
	v_mfma_f32_16x16x32_bf16 v[116:119], v[172:175], v[188:191], v[116:119]
	v_mfma_f32_16x16x32_bf16 v[108:111], v[180:183], v[188:191], v[108:111]
	v_mfma_f32_16x16x32_bf16 v[100:103], v[172:175], v[196:199], v[100:103]
	v_mfma_f32_16x16x32_bf16 v[92:95], v[180:183], v[196:199], v[92:95]
	v_mfma_f32_16x16x32_bf16 v[84:87], v[172:175], v[204:207], v[84:87]
	v_mfma_f32_16x16x32_bf16 v[76:79], v[180:183], v[204:207], v[76:79]
	v_mfma_f32_16x16x32_bf16 v[68:71], v[172:175], v[212:215], v[68:71]
	v_mfma_f32_16x16x32_bf16 v[64:67], v[180:183], v[212:215], v[64:67]
	s_setprio 0
	s_barrier
	s_add_i32 s65, s53, s45
	v_lshl_add_u64 v[144:145], s[36:37], 0, v[130:131]
	s_mov_b32 m0, s65
	ds_read_b128 v[184:187], v151 offset:16384
	ds_read_b128 v[188:191], v151 offset:17408
	ds_read_b128 v[192:195], v151 offset:18432
	ds_read_b128 v[196:199], v151 offset:19456
	ds_read_b128 v[200:203], v151 offset:20480
	ds_read_b128 v[204:207], v151 offset:21504
	ds_read_b128 v[208:211], v151 offset:22528
	ds_read_b128 v[212:215], v151 offset:23552
	global_load_lds_dwordx4 v[144:145], off
	s_add_i32 m0, s65, 0x2000
	s_add_u32 s66, s36, 0x400000
	v_lshl_add_u64 v[216:217], s[36:37], 0, v[134:135]
	s_addc_u32 s67, s37, 0
	s_add_i32 s65, s54, s45
	global_load_lds_dwordx4 v[216:217], off
	v_lshl_add_u64 v[218:219], s[66:67], 0, v[130:131]
	s_mov_b32 m0, s65
	v_lshl_add_u64 v[220:221], s[38:39], 0, v[132:133]
	global_load_lds_dwordx4 v[218:219], off
	v_lshl_add_u64 v[218:219], s[66:67], 0, v[134:135]
	s_add_i32 m0, s65, 0x2000
	s_nop 0
	global_load_lds_dwordx4 v[218:219], off
	v_lshl_add_u64 v[218:219], s[38:39], 0, v[128:129]
	s_mov_b32 m0, s31
	s_nop 0
	global_load_lds_dwordx4 v[218:219], off
	s_mov_b32 m0, s46
	s_nop 0
	global_load_lds_dwordx4 v[220:221], off
	s_waitcnt vmcnt(8)
	s_waitcnt lgkmcnt(0)
	s_barrier
	s_setprio 1
	v_mfma_f32_16x16x32_bf16 v[60:63], v[152:155], v[184:187], v[60:63]
	v_mfma_f32_16x16x32_bf16 v[56:59], v[160:163], v[184:187], v[56:59]
	v_mfma_f32_16x16x32_bf16 v[44:47], v[152:155], v[192:195], v[44:47]
	v_mfma_f32_16x16x32_bf16 v[40:43], v[160:163], v[192:195], v[40:43]
	v_mfma_f32_16x16x32_bf16 v[28:31], v[152:155], v[200:203], v[28:31]
	v_mfma_f32_16x16x32_bf16 v[24:27], v[160:163], v[200:203], v[24:27]
	v_mfma_f32_16x16x32_bf16 v[12:15], v[152:155], v[208:211], v[12:15]
	v_mfma_f32_16x16x32_bf16 v[8:11], v[160:163], v[208:211], v[8:11]
	v_mfma_f32_16x16x32_bf16 v[60:63], v[156:159], v[188:191], v[60:63]
	v_mfma_f32_16x16x32_bf16 v[56:59], v[164:167], v[188:191], v[56:59]
	v_mfma_f32_16x16x32_bf16 v[44:47], v[156:159], v[196:199], v[44:47]
	v_mfma_f32_16x16x32_bf16 v[40:43], v[164:167], v[196:199], v[40:43]
	v_mfma_f32_16x16x32_bf16 v[28:31], v[156:159], v[204:207], v[28:31]
	v_mfma_f32_16x16x32_bf16 v[24:27], v[164:167], v[204:207], v[24:27]
	v_mfma_f32_16x16x32_bf16 v[12:15], v[156:159], v[212:215], v[12:15]
	v_mfma_f32_16x16x32_bf16 v[8:11], v[164:167], v[212:215], v[8:11]
	s_setprio 0
	s_setprio 1
	v_mfma_f32_16x16x32_bf16 v[52:55], v[168:171], v[184:187], v[52:55]
	v_mfma_f32_16x16x32_bf16 v[48:51], v[176:179], v[184:187], v[48:51]
	v_mfma_f32_16x16x32_bf16 v[36:39], v[168:171], v[192:195], v[36:39]
	v_mfma_f32_16x16x32_bf16 v[32:35], v[176:179], v[192:195], v[32:35]
	v_mfma_f32_16x16x32_bf16 v[20:23], v[168:171], v[200:203], v[20:23]
	v_mfma_f32_16x16x32_bf16 v[16:19], v[176:179], v[200:203], v[16:19]
	v_mfma_f32_16x16x32_bf16 v[4:7], v[168:171], v[208:211], v[4:7]
	v_mfma_f32_16x16x32_bf16 v[0:3], v[176:179], v[208:211], v[0:3]
	v_mfma_f32_16x16x32_bf16 v[52:55], v[172:175], v[188:191], v[52:55]
	v_mfma_f32_16x16x32_bf16 v[48:51], v[180:183], v[188:191], v[48:51]
	v_mfma_f32_16x16x32_bf16 v[36:39], v[172:175], v[196:199], v[36:39]
	v_mfma_f32_16x16x32_bf16 v[32:35], v[180:183], v[196:199], v[32:35]
	v_mfma_f32_16x16x32_bf16 v[20:23], v[172:175], v[204:207], v[20:23]
	v_mfma_f32_16x16x32_bf16 v[16:19], v[180:183], v[204:207], v[16:19]
	v_mfma_f32_16x16x32_bf16 v[4:7], v[172:175], v[212:215], v[4:7]
	v_mfma_f32_16x16x32_bf16 v[0:3], v[180:183], v[212:215], v[0:3]
	s_setprio 0
	s_barrier
	s_add_i32 s65, 0, 0x18000
	s_add_i32 s66, 0, 0x1c000
	v_add_u32_e32 v164, s65, v147
	v_add_u32_e32 v180, s66, v147
	ds_read_b128 v[152:155], v164
	ds_read_b128 v[156:159], v164 offset:1024
	ds_read_b128 v[160:163], v164 offset:2048
	ds_read_b128 v[164:167], v164 offset:3072
	ds_read_b128 v[168:171], v180
	ds_read_b128 v[172:175], v180 offset:1024
	ds_read_b128 v[176:179], v180 offset:2048
	ds_read_b128 v[180:183], v180 offset:3072
	s_add_u32 s38, s38, 0x400000
	s_addc_u32 s39, s39, 0
	s_mov_b32 m0, s47
	v_lshl_add_u64 v[222:223], s[38:39], 0, v[128:129]
	ds_read_b128 v[184:187], v151 offset:32768
	ds_read_b128 v[188:191], v151 offset:33792
	ds_read_b128 v[192:195], v151 offset:34816
	ds_read_b128 v[196:199], v151 offset:35840
	ds_read_b128 v[200:203], v151 offset:36864
	ds_read_b128 v[204:207], v151 offset:37888
	ds_read_b128 v[208:211], v151 offset:38912
	ds_read_b128 v[212:215], v151 offset:39936
	global_load_lds_dwordx4 v[222:223], off
	v_lshl_add_u64 v[222:223], s[38:39], 0, v[132:133]
	s_mov_b32 m0, s48
	s_nop 0
	global_load_lds_dwordx4 v[222:223], off
	s_waitcnt vmcnt(8)
	s_waitcnt lgkmcnt(0)
	s_barrier
	s_setprio 1
	v_mfma_f32_16x16x32_bf16 v[124:127], v[152:155], v[184:187], v[124:127]
	v_mfma_f32_16x16x32_bf16 v[120:123], v[160:163], v[184:187], v[120:123]
	v_mfma_f32_16x16x32_bf16 v[112:115], v[152:155], v[192:195], v[112:115]
	v_mfma_f32_16x16x32_bf16 v[104:107], v[160:163], v[192:195], v[104:107]
	v_mfma_f32_16x16x32_bf16 v[96:99], v[152:155], v[200:203], v[96:99]
	v_mfma_f32_16x16x32_bf16 v[88:91], v[160:163], v[200:203], v[88:91]
	v_mfma_f32_16x16x32_bf16 v[80:83], v[152:155], v[208:211], v[80:83]
	v_mfma_f32_16x16x32_bf16 v[72:75], v[160:163], v[208:211], v[72:75]
	v_mfma_f32_16x16x32_bf16 v[124:127], v[156:159], v[188:191], v[124:127]
	v_mfma_f32_16x16x32_bf16 v[120:123], v[164:167], v[188:191], v[120:123]
	v_mfma_f32_16x16x32_bf16 v[112:115], v[156:159], v[196:199], v[112:115]
	v_mfma_f32_16x16x32_bf16 v[104:107], v[164:167], v[196:199], v[104:107]
	v_mfma_f32_16x16x32_bf16 v[96:99], v[156:159], v[204:207], v[96:99]
	v_mfma_f32_16x16x32_bf16 v[88:91], v[164:167], v[204:207], v[88:91]
	v_mfma_f32_16x16x32_bf16 v[80:83], v[156:159], v[212:215], v[80:83]
	v_mfma_f32_16x16x32_bf16 v[72:75], v[164:167], v[212:215], v[72:75]
	s_setprio 0
	s_setprio 1
	v_mfma_f32_16x16x32_bf16 v[116:119], v[168:171], v[184:187], v[116:119]
	v_mfma_f32_16x16x32_bf16 v[108:111], v[176:179], v[184:187], v[108:111]
	v_mfma_f32_16x16x32_bf16 v[100:103], v[168:171], v[192:195], v[100:103]
	v_mfma_f32_16x16x32_bf16 v[92:95], v[176:179], v[192:195], v[92:95]
	v_mfma_f32_16x16x32_bf16 v[84:87], v[168:171], v[200:203], v[84:87]
	v_mfma_f32_16x16x32_bf16 v[76:79], v[176:179], v[200:203], v[76:79]
	v_mfma_f32_16x16x32_bf16 v[68:71], v[168:171], v[208:211], v[68:71]
	v_mfma_f32_16x16x32_bf16 v[64:67], v[176:179], v[208:211], v[64:67]
	v_mfma_f32_16x16x32_bf16 v[116:119], v[172:175], v[188:191], v[116:119]
	v_mfma_f32_16x16x32_bf16 v[108:111], v[180:183], v[188:191], v[108:111]
	v_mfma_f32_16x16x32_bf16 v[100:103], v[172:175], v[196:199], v[100:103]
	v_mfma_f32_16x16x32_bf16 v[92:95], v[180:183], v[196:199], v[92:95]
	v_mfma_f32_16x16x32_bf16 v[84:87], v[172:175], v[204:207], v[84:87]
	v_mfma_f32_16x16x32_bf16 v[76:79], v[180:183], v[204:207], v[76:79]
	v_mfma_f32_16x16x32_bf16 v[68:71], v[172:175], v[212:215], v[68:71]
	v_mfma_f32_16x16x32_bf16 v[64:67], v[180:183], v[212:215], v[64:67]
	s_setprio 0
	s_barrier
	s_add_i32 s38, s65, s45
	v_lshl_add_u64 v[144:145], v[144:145], 0, s[10:11]
	s_mov_b32 m0, s38
	ds_read_b128 v[184:187], v151 offset:49152
	ds_read_b128 v[188:191], v151 offset:50176
	ds_read_b128 v[192:195], v151 offset:51200
	ds_read_b128 v[196:199], v151 offset:52224
	ds_read_b128 v[200:203], v151 offset:53248
	ds_read_b128 v[204:207], v151 offset:54272
	ds_read_b128 v[208:211], v151 offset:55296
	ds_read_b128 v[212:215], v151 offset:56320
	global_load_lds_dwordx4 v[144:145], off
	s_add_i32 m0, s38, 0x2000
	s_add_u32 s36, s36, 0x400080
	v_lshl_add_u64 v[144:145], v[216:217], 0, s[10:11]
	s_addc_u32 s37, s37, 0
	s_add_i32 s38, s66, s45
	global_load_lds_dwordx4 v[144:145], off
	v_lshl_add_u64 v[144:145], s[36:37], 0, v[130:131]
	s_mov_b32 m0, s38
	s_nop 0
	global_load_lds_dwordx4 v[144:145], off
	v_lshl_add_u64 v[144:145], s[36:37], 0, v[134:135]
	s_add_i32 m0, s38, 0x2000
	s_nop 0
	global_load_lds_dwordx4 v[144:145], off
	v_lshl_add_u64 v[144:145], v[218:219], 0, s[10:11]
	s_mov_b32 m0, s50
	s_nop 0
	global_load_lds_dwordx4 v[144:145], off
	v_lshl_add_u64 v[144:145], v[220:221], 0, s[10:11]
	s_mov_b32 m0, s51
	s_nop 0
	global_load_lds_dwordx4 v[144:145], off
	s_waitcnt vmcnt(8)
	s_waitcnt lgkmcnt(0)
	s_barrier
	s_setprio 1
	v_mfma_f32_16x16x32_bf16 v[60:63], v[152:155], v[184:187], v[60:63]
	v_mfma_f32_16x16x32_bf16 v[56:59], v[160:163], v[184:187], v[56:59]
	v_mfma_f32_16x16x32_bf16 v[44:47], v[152:155], v[192:195], v[44:47]
	v_mfma_f32_16x16x32_bf16 v[40:43], v[160:163], v[192:195], v[40:43]
	v_mfma_f32_16x16x32_bf16 v[28:31], v[152:155], v[200:203], v[28:31]
	v_mfma_f32_16x16x32_bf16 v[24:27], v[160:163], v[200:203], v[24:27]
	v_mfma_f32_16x16x32_bf16 v[12:15], v[152:155], v[208:211], v[12:15]
	v_mfma_f32_16x16x32_bf16 v[8:11], v[160:163], v[208:211], v[8:11]
	v_mfma_f32_16x16x32_bf16 v[60:63], v[156:159], v[188:191], v[60:63]
	v_mfma_f32_16x16x32_bf16 v[56:59], v[164:167], v[188:191], v[56:59]
	v_mfma_f32_16x16x32_bf16 v[44:47], v[156:159], v[196:199], v[44:47]
	v_mfma_f32_16x16x32_bf16 v[40:43], v[164:167], v[196:199], v[40:43]
	v_mfma_f32_16x16x32_bf16 v[28:31], v[156:159], v[204:207], v[28:31]
	v_mfma_f32_16x16x32_bf16 v[24:27], v[164:167], v[204:207], v[24:27]
	v_mfma_f32_16x16x32_bf16 v[12:15], v[156:159], v[212:215], v[12:15]
	v_mfma_f32_16x16x32_bf16 v[8:11], v[164:167], v[212:215], v[8:11]
	s_setprio 0
	s_setprio 1
	v_mfma_f32_16x16x32_bf16 v[52:55], v[168:171], v[184:187], v[52:55]
	v_mfma_f32_16x16x32_bf16 v[48:51], v[176:179], v[184:187], v[48:51]
	v_mfma_f32_16x16x32_bf16 v[36:39], v[168:171], v[192:195], v[36:39]
	v_mfma_f32_16x16x32_bf16 v[32:35], v[176:179], v[192:195], v[32:35]
	v_mfma_f32_16x16x32_bf16 v[20:23], v[168:171], v[200:203], v[20:23]
	v_mfma_f32_16x16x32_bf16 v[16:19], v[176:179], v[200:203], v[16:19]
	v_mfma_f32_16x16x32_bf16 v[4:7], v[168:171], v[208:211], v[4:7]
	v_mfma_f32_16x16x32_bf16 v[0:3], v[176:179], v[208:211], v[0:3]
	v_mfma_f32_16x16x32_bf16 v[52:55], v[172:175], v[188:191], v[52:55]
	v_mfma_f32_16x16x32_bf16 v[48:51], v[180:183], v[188:191], v[48:51]
	v_mfma_f32_16x16x32_bf16 v[36:39], v[172:175], v[196:199], v[36:39]
	v_mfma_f32_16x16x32_bf16 v[32:35], v[180:183], v[196:199], v[32:35]
	v_mfma_f32_16x16x32_bf16 v[20:23], v[172:175], v[204:207], v[20:23]
	v_mfma_f32_16x16x32_bf16 v[16:19], v[180:183], v[204:207], v[16:19]
	v_mfma_f32_16x16x32_bf16 v[4:7], v[172:175], v[212:215], v[4:7]
	v_mfma_f32_16x16x32_bf16 v[0:3], v[180:183], v[212:215], v[0:3]
	s_setprio 0
	s_add_i32 s64, s64, 2
	s_add_u32 s62, s62, 0x100
	s_addc_u32 s63, s63, 0
	s_add_u32 s34, s34, 0x100
	s_addc_u32 s35, s35, 0
	s_cmpk_gt_u32 s64, 0xfd
	s_barrier
	s_cbranch_scc0 .LBB0_3161
	s_and_b64 vcc, exec, s[12:13]
	s_cbranch_vccz .LBB0_3164
	s_barrier
